# conditioning GEMV k-loop hand-pipelined: 32 weight-row loads in flight behind counted vmcnt instead of vmcnt(0) after each (same f32 FMA order)
# speedup vs baseline: 1.0096x; 1.0096x over previous
; __device__ __forceinline__ void ada_phase(LAS unsigned char* lds, const float* c, const float* c_ctx, const float* ada_w, const float* ada_b, float* mods, int G, int bid, int tid, int item0, int item1) {
;     ...
;     for (int item = item0 + bid; item < item1; item += G) {
;         const int l = item / 384, n0 = (item % 384) * 32;
;         const float* wp = ada_w + (size_t)l * D * MODW + n0 + 4 * cgp;
;         f32x4 acc[9];
; #pragma unroll
;         for (int r = 0; r < 9; ++r) acc[r] = (f32x4){0.f, 0.f, 0.f, 0.f};
; #pragma unroll 16
;         for (int i = 0; i < 32; ++i) { const int k = ks + 64 * i; const f32x4 w = *(const f32x4*)(wp + (size_t)k * MODW);
; #pragma unroll
;             for (int r = 0; r < 9; ++r) acc[r] += w * sT[k * 9 + r]; }
.Lada_k:
	v_lshl_add_u64 v[26:27], v[8:9], 0, s[14:15]
	global_load_dwordx4 v[60:63], v[26:27], off
	s_add_u32 s14, s14, 0x300000
	s_addc_u32 s15, s15, 0
	v_lshl_add_u64 v[26:27], v[8:9], 0, s[14:15]
	global_load_dwordx4 v[64:67], v[26:27], off
	s_add_u32 s14, s14, 0x300000
	s_addc_u32 s15, s15, 0
	v_lshl_add_u64 v[26:27], v[8:9], 0, s[14:15]
	global_load_dwordx4 v[68:71], v[26:27], off
	s_add_u32 s14, s14, 0x300000
	s_addc_u32 s15, s15, 0
	v_lshl_add_u64 v[26:27], v[8:9], 0, s[14:15]
	global_load_dwordx4 v[72:75], v[26:27], off
	s_add_u32 s14, s14, 0x300000
	s_addc_u32 s15, s15, 0
	v_lshl_add_u64 v[26:27], v[8:9], 0, s[14:15]
	global_load_dwordx4 v[76:79], v[26:27], off
	s_add_u32 s14, s14, 0x300000
	s_addc_u32 s15, s15, 0
	v_lshl_add_u64 v[26:27], v[8:9], 0, s[14:15]
	global_load_dwordx4 v[84:87], v[26:27], off
	s_add_u32 s14, s14, 0x300000
	s_addc_u32 s15, s15, 0
	v_lshl_add_u64 v[26:27], v[8:9], 0, s[14:15]
	global_load_dwordx4 v[88:91], v[26:27], off
	s_add_u32 s14, s14, 0x300000
	s_addc_u32 s15, s15, 0
	v_lshl_add_u64 v[26:27], v[8:9], 0, s[14:15]
	global_load_dwordx4 v[92:95], v[26:27], off
	s_add_u32 s14, s14, 0x300000
	s_addc_u32 s15, s15, 0
	v_lshl_add_u64 v[26:27], v[8:9], 0, s[14:15]
	global_load_dwordx4 v[100:103], v[26:27], off
	s_add_u32 s14, s14, 0x300000
	s_addc_u32 s15, s15, 0
	v_lshl_add_u64 v[26:27], v[8:9], 0, s[14:15]
	global_load_dwordx4 v[104:107], v[26:27], off
	s_add_u32 s14, s14, 0x300000
	s_addc_u32 s15, s15, 0
	v_lshl_add_u64 v[26:27], v[8:9], 0, s[14:15]
	global_load_dwordx4 v[108:111], v[26:27], off
	s_add_u32 s14, s14, 0x300000
	s_addc_u32 s15, s15, 0
	v_lshl_add_u64 v[26:27], v[8:9], 0, s[14:15]
	global_load_dwordx4 v[112:115], v[26:27], off
	s_add_u32 s14, s14, 0x300000
	s_addc_u32 s15, s15, 0
	v_lshl_add_u64 v[26:27], v[8:9], 0, s[14:15]
	global_load_dwordx4 v[116:119], v[26:27], off
	s_add_u32 s14, s14, 0x300000
	s_addc_u32 s15, s15, 0
	v_lshl_add_u64 v[26:27], v[8:9], 0, s[14:15]
	global_load_dwordx4 v[120:123], v[26:27], off
	s_add_u32 s14, s14, 0x300000
	s_addc_u32 s15, s15, 0
	v_lshl_add_u64 v[26:27], v[8:9], 0, s[14:15]
	global_load_dwordx4 v[124:127], v[26:27], off
	s_add_u32 s14, s14, 0x300000
	s_addc_u32 s15, s15, 0
	v_lshl_add_u64 v[26:27], v[8:9], 0, s[14:15]
	global_load_dwordx4 v[128:131], v[26:27], off
	s_add_u32 s14, s14, 0x300000
	s_addc_u32 s15, s15, 0
	v_lshl_add_u64 v[26:27], v[8:9], 0, s[14:15]
	global_load_dwordx4 v[132:135], v[26:27], off
	s_add_u32 s14, s14, 0x300000
	s_addc_u32 s15, s15, 0
	v_lshl_add_u64 v[26:27], v[8:9], 0, s[14:15]
	global_load_dwordx4 v[136:139], v[26:27], off
	s_add_u32 s14, s14, 0x300000
	s_addc_u32 s15, s15, 0
	v_lshl_add_u64 v[26:27], v[8:9], 0, s[14:15]
	global_load_dwordx4 v[140:143], v[26:27], off
	s_add_u32 s14, s14, 0x300000
	s_addc_u32 s15, s15, 0
	v_lshl_add_u64 v[26:27], v[8:9], 0, s[14:15]
	global_load_dwordx4 v[144:147], v[26:27], off
	s_add_u32 s14, s14, 0x300000
	s_addc_u32 s15, s15, 0
	v_lshl_add_u64 v[26:27], v[8:9], 0, s[14:15]
	global_load_dwordx4 v[148:151], v[26:27], off
	s_add_u32 s14, s14, 0x300000
	s_addc_u32 s15, s15, 0
	v_lshl_add_u64 v[26:27], v[8:9], 0, s[14:15]
	global_load_dwordx4 v[152:155], v[26:27], off
	s_add_u32 s14, s14, 0x300000
	s_addc_u32 s15, s15, 0
	v_lshl_add_u64 v[26:27], v[8:9], 0, s[14:15]
	global_load_dwordx4 v[156:159], v[26:27], off
	s_add_u32 s14, s14, 0x300000
	s_addc_u32 s15, s15, 0
	v_lshl_add_u64 v[26:27], v[8:9], 0, s[14:15]
	global_load_dwordx4 v[160:163], v[26:27], off
	s_add_u32 s14, s14, 0x300000
	s_addc_u32 s15, s15, 0
	v_lshl_add_u64 v[26:27], v[8:9], 0, s[14:15]
	global_load_dwordx4 v[168:171], v[26:27], off
	s_add_u32 s14, s14, 0x300000
	s_addc_u32 s15, s15, 0
	v_lshl_add_u64 v[26:27], v[8:9], 0, s[14:15]
	global_load_dwordx4 v[172:175], v[26:27], off
	s_add_u32 s14, s14, 0x300000
	s_addc_u32 s15, s15, 0
	v_lshl_add_u64 v[26:27], v[8:9], 0, s[14:15]
	global_load_dwordx4 v[176:179], v[26:27], off
	s_add_u32 s14, s14, 0x300000
	s_addc_u32 s15, s15, 0
	v_lshl_add_u64 v[26:27], v[8:9], 0, s[14:15]
	global_load_dwordx4 v[180:183], v[26:27], off
	s_add_u32 s14, s14, 0x300000
	s_addc_u32 s15, s15, 0
	v_lshl_add_u64 v[26:27], v[8:9], 0, s[14:15]
	global_load_dwordx4 v[184:187], v[26:27], off
	s_add_u32 s14, s14, 0x300000
	s_addc_u32 s15, s15, 0
	v_lshl_add_u64 v[26:27], v[8:9], 0, s[14:15]
	global_load_dwordx4 v[188:191], v[26:27], off
	s_add_u32 s14, s14, 0x300000
	s_addc_u32 s15, s15, 0
	v_lshl_add_u64 v[26:27], v[8:9], 0, s[14:15]
	global_load_dwordx4 v[192:195], v[26:27], off
	s_add_u32 s14, s14, 0x300000
	s_addc_u32 s15, s15, 0
	v_lshl_add_u64 v[26:27], v[8:9], 0, s[14:15]
	global_load_dwordx4 v[196:199], v[26:27], off
	s_add_u32 s14, s14, 0x300000
	s_addc_u32 s15, s15, 0
	ds_read2_b32 v[50:51], v48 offset1:1
	ds_read2_b32 v[52:53], v48 offset0:2 offset1:3
	ds_read2_b32 v[54:55], v48 offset0:4 offset1:5
	ds_read2_b32 v[56:57], v48 offset0:6 offset1:7
	ds_read_b32 v58, v48 offset:32
	v_add_u32_e32 v27, 0x900, v48
	ds_read2_b32 v[200:201], v27 offset1:1
	ds_read2_b32 v[202:203], v27 offset0:2 offset1:3
	ds_read2_b32 v[204:205], v27 offset0:4 offset1:5
	ds_read2_b32 v[206:207], v27 offset0:6 offset1:7
	ds_read_b32 v208, v27 offset:32
	s_waitcnt vmcnt(31) lgkmcnt(5)
; __device__ __forceinline__ void ada_phase(LAS unsigned char* lds, const float* c, const float* c_ctx, const float* ada_w, const float* ada_b, float* mods, int G, int bid, int tid, int item0, int item1) {
;     ...
; #pragma unroll 16
;         for (int i = 0; i < 32; ++i) { const int k = ks + 64 * i; const f32x4 w = *(const f32x4*)(wp + (size_t)k * MODW);
; #pragma unroll
;             for (int r = 0; r < 9; ++r) acc[r] += w * sT[k * 9 + r]; }
	v_pk_fma_f32 v[46:47], v[60:61], v[50:51], v[46:47] op_sel_hi:[1,0,1]
	v_pk_fma_f32 v[44:45], v[62:63], v[50:51], v[44:45] op_sel_hi:[1,0,1]
	v_pk_fma_f32 v[42:43], v[60:61], v[50:51], v[42:43] op_sel:[0,1,0]
	v_pk_fma_f32 v[40:41], v[62:63], v[50:51], v[40:41] op_sel:[0,1,0]
	v_pk_fma_f32 v[38:39], v[60:61], v[52:53], v[38:39] op_sel_hi:[1,0,1]
	v_pk_fma_f32 v[36:37], v[62:63], v[52:53], v[36:37] op_sel_hi:[1,0,1]
	v_pk_fma_f32 v[34:35], v[60:61], v[52:53], v[34:35] op_sel:[0,1,0]
	v_pk_fma_f32 v[32:33], v[62:63], v[52:53], v[32:33] op_sel:[0,1,0]
	v_pk_fma_f32 v[30:31], v[60:61], v[54:55], v[30:31] op_sel_hi:[1,0,1]
	v_pk_fma_f32 v[28:29], v[62:63], v[54:55], v[28:29] op_sel_hi:[1,0,1]
	v_pk_fma_f32 v[24:25], v[60:61], v[54:55], v[24:25] op_sel:[0,1,0]
	v_pk_fma_f32 v[22:23], v[62:63], v[54:55], v[22:23] op_sel:[0,1,0]
	v_pk_fma_f32 v[20:21], v[60:61], v[56:57], v[20:21] op_sel_hi:[1,0,1]
	v_pk_fma_f32 v[18:19], v[62:63], v[56:57], v[18:19] op_sel_hi:[1,0,1]
	v_pk_fma_f32 v[16:17], v[60:61], v[56:57], v[16:17] op_sel:[0,1,0]
	v_pk_fma_f32 v[14:15], v[62:63], v[56:57], v[14:15] op_sel:[0,1,0]
	v_pk_fma_f32 v[12:13], v[60:61], v[58:59], v[12:13] op_sel_hi:[1,0,1]
	v_pk_fma_f32 v[10:11], v[62:63], v[58:59], v[10:11] op_sel_hi:[1,0,1]
	v_add_u32_e32 v27, 0x1200, v48
	ds_read2_b32 v[50:51], v27 offset1:1
	ds_read2_b32 v[52:53], v27 offset0:2 offset1:3
	ds_read2_b32 v[54:55], v27 offset0:4 offset1:5
	ds_read2_b32 v[56:57], v27 offset0:6 offset1:7
	ds_read_b32 v58, v27 offset:32
	s_waitcnt vmcnt(30) lgkmcnt(5)
	v_pk_fma_f32 v[46:47], v[64:65], v[200:201], v[46:47] op_sel_hi:[1,0,1]
	v_pk_fma_f32 v[44:45], v[66:67], v[200:201], v[44:45] op_sel_hi:[1,0,1]
	v_pk_fma_f32 v[42:43], v[64:65], v[200:201], v[42:43] op_sel:[0,1,0]
	v_pk_fma_f32 v[40:41], v[66:67], v[200:201], v[40:41] op_sel:[0,1,0]
	v_pk_fma_f32 v[38:39], v[64:65], v[202:203], v[38:39] op_sel_hi:[1,0,1]
	v_pk_fma_f32 v[36:37], v[66:67], v[202:203], v[36:37] op_sel_hi:[1,0,1]
	v_pk_fma_f32 v[34:35], v[64:65], v[202:203], v[34:35] op_sel:[0,1,0]
	v_pk_fma_f32 v[32:33], v[66:67], v[202:203], v[32:33] op_sel:[0,1,0]
	v_pk_fma_f32 v[30:31], v[64:65], v[204:205], v[30:31] op_sel_hi:[1,0,1]
	v_pk_fma_f32 v[28:29], v[66:67], v[204:205], v[28:29] op_sel_hi:[1,0,1]
	v_pk_fma_f32 v[24:25], v[64:65], v[204:205], v[24:25] op_sel:[0,1,0]
	v_pk_fma_f32 v[22:23], v[66:67], v[204:205], v[22:23] op_sel:[0,1,0]
	v_pk_fma_f32 v[20:21], v[64:65], v[206:207], v[20:21] op_sel_hi:[1,0,1]
	v_pk_fma_f32 v[18:19], v[66:67], v[206:207], v[18:19] op_sel_hi:[1,0,1]
	v_pk_fma_f32 v[16:17], v[64:65], v[206:207], v[16:17] op_sel:[0,1,0]
	v_pk_fma_f32 v[14:15], v[66:67], v[206:207], v[14:15] op_sel:[0,1,0]
	v_pk_fma_f32 v[12:13], v[64:65], v[208:209], v[12:13] op_sel_hi:[1,0,1]
	v_pk_fma_f32 v[10:11], v[66:67], v[208:209], v[10:11] op_sel_hi:[1,0,1]
	v_add_u32_e32 v27, 0x1b00, v48
	ds_read2_b32 v[200:201], v27 offset1:1
	ds_read2_b32 v[202:203], v27 offset0:2 offset1:3
	ds_read2_b32 v[204:205], v27 offset0:4 offset1:5
	ds_read2_b32 v[206:207], v27 offset0:6 offset1:7
	ds_read_b32 v208, v27 offset:32
	s_waitcnt vmcnt(29) lgkmcnt(5)
	v_pk_fma_f32 v[46:47], v[68:69], v[50:51], v[46:47] op_sel_hi:[1,0,1]
	v_pk_fma_f32 v[44:45], v[70:71], v[50:51], v[44:45] op_sel_hi:[1,0,1]
	v_pk_fma_f32 v[42:43], v[68:69], v[50:51], v[42:43] op_sel:[0,1,0]
	v_pk_fma_f32 v[40:41], v[70:71], v[50:51], v[40:41] op_sel:[0,1,0]
	v_pk_fma_f32 v[38:39], v[68:69], v[52:53], v[38:39] op_sel_hi:[1,0,1]
	v_pk_fma_f32 v[36:37], v[70:71], v[52:53], v[36:37] op_sel_hi:[1,0,1]
	v_pk_fma_f32 v[34:35], v[68:69], v[52:53], v[34:35] op_sel:[0,1,0]
	v_pk_fma_f32 v[32:33], v[70:71], v[52:53], v[32:33] op_sel:[0,1,0]
	v_pk_fma_f32 v[30:31], v[68:69], v[54:55], v[30:31] op_sel_hi:[1,0,1]
	v_pk_fma_f32 v[28:29], v[70:71], v[54:55], v[28:29] op_sel_hi:[1,0,1]
	v_pk_fma_f32 v[24:25], v[68:69], v[54:55], v[24:25] op_sel:[0,1,0]
	v_pk_fma_f32 v[22:23], v[70:71], v[54:55], v[22:23] op_sel:[0,1,0]
	v_pk_fma_f32 v[20:21], v[68:69], v[56:57], v[20:21] op_sel_hi:[1,0,1]
	v_pk_fma_f32 v[18:19], v[70:71], v[56:57], v[18:19] op_sel_hi:[1,0,1]
	v_pk_fma_f32 v[16:17], v[68:69], v[56:57], v[16:17] op_sel:[0,1,0]
	v_pk_fma_f32 v[14:15], v[70:71], v[56:57], v[14:15] op_sel:[0,1,0]
	v_pk_fma_f32 v[12:13], v[68:69], v[58:59], v[12:13] op_sel_hi:[1,0,1]
	v_pk_fma_f32 v[10:11], v[70:71], v[58:59], v[10:11] op_sel_hi:[1,0,1]
	v_add_u32_e32 v27, 0x2400, v48
	ds_read2_b32 v[50:51], v27 offset1:1
	ds_read2_b32 v[52:53], v27 offset0:2 offset1:3
	ds_read2_b32 v[54:55], v27 offset0:4 offset1:5
	ds_read2_b32 v[56:57], v27 offset0:6 offset1:7
	ds_read_b32 v58, v27 offset:32
	s_waitcnt vmcnt(28) lgkmcnt(5)
	v_pk_fma_f32 v[46:47], v[72:73], v[200:201], v[46:47] op_sel_hi:[1,0,1]
	v_pk_fma_f32 v[44:45], v[74:75], v[200:201], v[44:45] op_sel_hi:[1,0,1]
	v_pk_fma_f32 v[42:43], v[72:73], v[200:201], v[42:43] op_sel:[0,1,0]
	v_pk_fma_f32 v[40:41], v[74:75], v[200:201], v[40:41] op_sel:[0,1,0]
	v_pk_fma_f32 v[38:39], v[72:73], v[202:203], v[38:39] op_sel_hi:[1,0,1]
	v_pk_fma_f32 v[36:37], v[74:75], v[202:203], v[36:37] op_sel_hi:[1,0,1]
	v_pk_fma_f32 v[34:35], v[72:73], v[202:203], v[34:35] op_sel:[0,1,0]
	v_pk_fma_f32 v[32:33], v[74:75], v[202:203], v[32:33] op_sel:[0,1,0]
	v_pk_fma_f32 v[30:31], v[72:73], v[204:205], v[30:31] op_sel_hi:[1,0,1]
	v_pk_fma_f32 v[28:29], v[74:75], v[204:205], v[28:29] op_sel_hi:[1,0,1]
	v_pk_fma_f32 v[24:25], v[72:73], v[204:205], v[24:25] op_sel:[0,1,0]
	v_pk_fma_f32 v[22:23], v[74:75], v[204:205], v[22:23] op_sel:[0,1,0]
	v_pk_fma_f32 v[20:21], v[72:73], v[206:207], v[20:21] op_sel_hi:[1,0,1]
	v_pk_fma_f32 v[18:19], v[74:75], v[206:207], v[18:19] op_sel_hi:[1,0,1]
	v_pk_fma_f32 v[16:17], v[72:73], v[206:207], v[16:17] op_sel:[0,1,0]
	v_pk_fma_f32 v[14:15], v[74:75], v[206:207], v[14:15] op_sel:[0,1,0]
	v_pk_fma_f32 v[12:13], v[72:73], v[208:209], v[12:13] op_sel_hi:[1,0,1]
	v_pk_fma_f32 v[10:11], v[74:75], v[208:209], v[10:11] op_sel_hi:[1,0,1]
	v_add_u32_e32 v27, 0x2d00, v48
	ds_read2_b32 v[200:201], v27 offset1:1
	ds_read2_b32 v[202:203], v27 offset0:2 offset1:3
	ds_read2_b32 v[204:205], v27 offset0:4 offset1:5
	ds_read2_b32 v[206:207], v27 offset0:6 offset1:7
	ds_read_b32 v208, v27 offset:32
	s_waitcnt vmcnt(27) lgkmcnt(5)
; __device__ __forceinline__ void ada_phase(LAS unsigned char* lds, const float* c, const float* c_ctx, const float* ada_w, const float* ada_b, float* mods, int G, int bid, int tid, int item0, int item1) {
;     ...
; #pragma unroll 16
;         for (int i = 0; i < 32; ++i) { const int k = ks + 64 * i; const f32x4 w = *(const f32x4*)(wp + (size_t)k * MODW);
; #pragma unroll
;             for (int r = 0; r < 9; ++r) acc[r] += w * sT[k * 9 + r]; }
	v_pk_fma_f32 v[46:47], v[76:77], v[50:51], v[46:47] op_sel_hi:[1,0,1]
	v_pk_fma_f32 v[44:45], v[78:79], v[50:51], v[44:45] op_sel_hi:[1,0,1]
	v_pk_fma_f32 v[42:43], v[76:77], v[50:51], v[42:43] op_sel:[0,1,0]
	v_pk_fma_f32 v[40:41], v[78:79], v[50:51], v[40:41] op_sel:[0,1,0]
	v_pk_fma_f32 v[38:39], v[76:77], v[52:53], v[38:39] op_sel_hi:[1,0,1]
	v_pk_fma_f32 v[36:37], v[78:79], v[52:53], v[36:37] op_sel_hi:[1,0,1]
	v_pk_fma_f32 v[34:35], v[76:77], v[52:53], v[34:35] op_sel:[0,1,0]
	v_pk_fma_f32 v[32:33], v[78:79], v[52:53], v[32:33] op_sel:[0,1,0]
	v_pk_fma_f32 v[30:31], v[76:77], v[54:55], v[30:31] op_sel_hi:[1,0,1]
	v_pk_fma_f32 v[28:29], v[78:79], v[54:55], v[28:29] op_sel_hi:[1,0,1]
	v_pk_fma_f32 v[24:25], v[76:77], v[54:55], v[24:25] op_sel:[0,1,0]
	v_pk_fma_f32 v[22:23], v[78:79], v[54:55], v[22:23] op_sel:[0,1,0]
	v_pk_fma_f32 v[20:21], v[76:77], v[56:57], v[20:21] op_sel_hi:[1,0,1]
	v_pk_fma_f32 v[18:19], v[78:79], v[56:57], v[18:19] op_sel_hi:[1,0,1]
	v_pk_fma_f32 v[16:17], v[76:77], v[56:57], v[16:17] op_sel:[0,1,0]
	v_pk_fma_f32 v[14:15], v[78:79], v[56:57], v[14:15] op_sel:[0,1,0]
	v_pk_fma_f32 v[12:13], v[76:77], v[58:59], v[12:13] op_sel_hi:[1,0,1]
	v_pk_fma_f32 v[10:11], v[78:79], v[58:59], v[10:11] op_sel_hi:[1,0,1]
	v_add_u32_e32 v27, 0x3600, v48
	ds_read2_b32 v[50:51], v27 offset1:1
	ds_read2_b32 v[52:53], v27 offset0:2 offset1:3
	ds_read2_b32 v[54:55], v27 offset0:4 offset1:5
	ds_read2_b32 v[56:57], v27 offset0:6 offset1:7
	ds_read_b32 v58, v27 offset:32
	s_waitcnt vmcnt(26) lgkmcnt(5)
	v_pk_fma_f32 v[46:47], v[84:85], v[200:201], v[46:47] op_sel_hi:[1,0,1]
	v_pk_fma_f32 v[44:45], v[86:87], v[200:201], v[44:45] op_sel_hi:[1,0,1]
	v_pk_fma_f32 v[42:43], v[84:85], v[200:201], v[42:43] op_sel:[0,1,0]
	v_pk_fma_f32 v[40:41], v[86:87], v[200:201], v[40:41] op_sel:[0,1,0]
	v_pk_fma_f32 v[38:39], v[84:85], v[202:203], v[38:39] op_sel_hi:[1,0,1]
	v_pk_fma_f32 v[36:37], v[86:87], v[202:203], v[36:37] op_sel_hi:[1,0,1]
	v_pk_fma_f32 v[34:35], v[84:85], v[202:203], v[34:35] op_sel:[0,1,0]
	v_pk_fma_f32 v[32:33], v[86:87], v[202:203], v[32:33] op_sel:[0,1,0]
	v_pk_fma_f32 v[30:31], v[84:85], v[204:205], v[30:31] op_sel_hi:[1,0,1]
	v_pk_fma_f32 v[28:29], v[86:87], v[204:205], v[28:29] op_sel_hi:[1,0,1]
	v_pk_fma_f32 v[24:25], v[84:85], v[204:205], v[24:25] op_sel:[0,1,0]
	v_pk_fma_f32 v[22:23], v[86:87], v[204:205], v[22:23] op_sel:[0,1,0]
	v_pk_fma_f32 v[20:21], v[84:85], v[206:207], v[20:21] op_sel_hi:[1,0,1]
	v_pk_fma_f32 v[18:19], v[86:87], v[206:207], v[18:19] op_sel_hi:[1,0,1]
	v_pk_fma_f32 v[16:17], v[84:85], v[206:207], v[16:17] op_sel:[0,1,0]
	v_pk_fma_f32 v[14:15], v[86:87], v[206:207], v[14:15] op_sel:[0,1,0]
	v_pk_fma_f32 v[12:13], v[84:85], v[208:209], v[12:13] op_sel_hi:[1,0,1]
	v_pk_fma_f32 v[10:11], v[86:87], v[208:209], v[10:11] op_sel_hi:[1,0,1]
	v_add_u32_e32 v27, 0x3f00, v48
	ds_read2_b32 v[200:201], v27 offset1:1
	ds_read2_b32 v[202:203], v27 offset0:2 offset1:3
	ds_read2_b32 v[204:205], v27 offset0:4 offset1:5
	ds_read2_b32 v[206:207], v27 offset0:6 offset1:7
	ds_read_b32 v208, v27 offset:32
	s_waitcnt vmcnt(25) lgkmcnt(5)
	v_pk_fma_f32 v[46:47], v[88:89], v[50:51], v[46:47] op_sel_hi:[1,0,1]
	v_pk_fma_f32 v[44:45], v[90:91], v[50:51], v[44:45] op_sel_hi:[1,0,1]
	v_pk_fma_f32 v[42:43], v[88:89], v[50:51], v[42:43] op_sel:[0,1,0]
	v_pk_fma_f32 v[40:41], v[90:91], v[50:51], v[40:41] op_sel:[0,1,0]
	v_pk_fma_f32 v[38:39], v[88:89], v[52:53], v[38:39] op_sel_hi:[1,0,1]
	v_pk_fma_f32 v[36:37], v[90:91], v[52:53], v[36:37] op_sel_hi:[1,0,1]
	v_pk_fma_f32 v[34:35], v[88:89], v[52:53], v[34:35] op_sel:[0,1,0]
	v_pk_fma_f32 v[32:33], v[90:91], v[52:53], v[32:33] op_sel:[0,1,0]
	v_pk_fma_f32 v[30:31], v[88:89], v[54:55], v[30:31] op_sel_hi:[1,0,1]
	v_pk_fma_f32 v[28:29], v[90:91], v[54:55], v[28:29] op_sel_hi:[1,0,1]
	v_pk_fma_f32 v[24:25], v[88:89], v[54:55], v[24:25] op_sel:[0,1,0]
	v_pk_fma_f32 v[22:23], v[90:91], v[54:55], v[22:23] op_sel:[0,1,0]
	v_pk_fma_f32 v[20:21], v[88:89], v[56:57], v[20:21] op_sel_hi:[1,0,1]
	v_pk_fma_f32 v[18:19], v[90:91], v[56:57], v[18:19] op_sel_hi:[1,0,1]
	v_pk_fma_f32 v[16:17], v[88:89], v[56:57], v[16:17] op_sel:[0,1,0]
	v_pk_fma_f32 v[14:15], v[90:91], v[56:57], v[14:15] op_sel:[0,1,0]
	v_pk_fma_f32 v[12:13], v[88:89], v[58:59], v[12:13] op_sel_hi:[1,0,1]
	v_pk_fma_f32 v[10:11], v[90:91], v[58:59], v[10:11] op_sel_hi:[1,0,1]
	v_add_u32_e32 v27, 0x4800, v48
	ds_read2_b32 v[50:51], v27 offset1:1
	ds_read2_b32 v[52:53], v27 offset0:2 offset1:3
	ds_read2_b32 v[54:55], v27 offset0:4 offset1:5
	ds_read2_b32 v[56:57], v27 offset0:6 offset1:7
	ds_read_b32 v58, v27 offset:32
	s_waitcnt vmcnt(24) lgkmcnt(5)
	v_pk_fma_f32 v[46:47], v[92:93], v[200:201], v[46:47] op_sel_hi:[1,0,1]
	v_pk_fma_f32 v[44:45], v[94:95], v[200:201], v[44:45] op_sel_hi:[1,0,1]
	v_pk_fma_f32 v[42:43], v[92:93], v[200:201], v[42:43] op_sel:[0,1,0]
	v_pk_fma_f32 v[40:41], v[94:95], v[200:201], v[40:41] op_sel:[0,1,0]
	v_pk_fma_f32 v[38:39], v[92:93], v[202:203], v[38:39] op_sel_hi:[1,0,1]
	v_pk_fma_f32 v[36:37], v[94:95], v[202:203], v[36:37] op_sel_hi:[1,0,1]
	v_pk_fma_f32 v[34:35], v[92:93], v[202:203], v[34:35] op_sel:[0,1,0]
	v_pk_fma_f32 v[32:33], v[94:95], v[202:203], v[32:33] op_sel:[0,1,0]
	v_pk_fma_f32 v[30:31], v[92:93], v[204:205], v[30:31] op_sel_hi:[1,0,1]
	v_pk_fma_f32 v[28:29], v[94:95], v[204:205], v[28:29] op_sel_hi:[1,0,1]
	v_pk_fma_f32 v[24:25], v[92:93], v[204:205], v[24:25] op_sel:[0,1,0]
	v_pk_fma_f32 v[22:23], v[94:95], v[204:205], v[22:23] op_sel:[0,1,0]
	v_pk_fma_f32 v[20:21], v[92:93], v[206:207], v[20:21] op_sel_hi:[1,0,1]
	v_pk_fma_f32 v[18:19], v[94:95], v[206:207], v[18:19] op_sel_hi:[1,0,1]
	v_pk_fma_f32 v[16:17], v[92:93], v[206:207], v[16:17] op_sel:[0,1,0]
	v_pk_fma_f32 v[14:15], v[94:95], v[206:207], v[14:15] op_sel:[0,1,0]
	v_pk_fma_f32 v[12:13], v[92:93], v[208:209], v[12:13] op_sel_hi:[1,0,1]
	v_pk_fma_f32 v[10:11], v[94:95], v[208:209], v[10:11] op_sel_hi:[1,0,1]
	v_add_u32_e32 v27, 0x5100, v48
	ds_read2_b32 v[200:201], v27 offset1:1
	ds_read2_b32 v[202:203], v27 offset0:2 offset1:3
	ds_read2_b32 v[204:205], v27 offset0:4 offset1:5
	ds_read2_b32 v[206:207], v27 offset0:6 offset1:7
	ds_read_b32 v208, v27 offset:32
	s_waitcnt vmcnt(23) lgkmcnt(5)
; __device__ __forceinline__ void ada_phase(LAS unsigned char* lds, const float* c, const float* c_ctx, const float* ada_w, const float* ada_b, float* mods, int G, int bid, int tid, int item0, int item1) {
;     ...
; #pragma unroll 16
;         for (int i = 0; i < 32; ++i) { const int k = ks + 64 * i; const f32x4 w = *(const f32x4*)(wp + (size_t)k * MODW);
; #pragma unroll
;             for (int r = 0; r < 9; ++r) acc[r] += w * sT[k * 9 + r]; }
	v_pk_fma_f32 v[46:47], v[100:101], v[50:51], v[46:47] op_sel_hi:[1,0,1]
	v_pk_fma_f32 v[44:45], v[102:103], v[50:51], v[44:45] op_sel_hi:[1,0,1]
	v_pk_fma_f32 v[42:43], v[100:101], v[50:51], v[42:43] op_sel:[0,1,0]
	v_pk_fma_f32 v[40:41], v[102:103], v[50:51], v[40:41] op_sel:[0,1,0]
	v_pk_fma_f32 v[38:39], v[100:101], v[52:53], v[38:39] op_sel_hi:[1,0,1]
	v_pk_fma_f32 v[36:37], v[102:103], v[52:53], v[36:37] op_sel_hi:[1,0,1]
	v_pk_fma_f32 v[34:35], v[100:101], v[52:53], v[34:35] op_sel:[0,1,0]
	v_pk_fma_f32 v[32:33], v[102:103], v[52:53], v[32:33] op_sel:[0,1,0]
	v_pk_fma_f32 v[30:31], v[100:101], v[54:55], v[30:31] op_sel_hi:[1,0,1]
	v_pk_fma_f32 v[28:29], v[102:103], v[54:55], v[28:29] op_sel_hi:[1,0,1]
	v_pk_fma_f32 v[24:25], v[100:101], v[54:55], v[24:25] op_sel:[0,1,0]
	v_pk_fma_f32 v[22:23], v[102:103], v[54:55], v[22:23] op_sel:[0,1,0]
	v_pk_fma_f32 v[20:21], v[100:101], v[56:57], v[20:21] op_sel_hi:[1,0,1]
	v_pk_fma_f32 v[18:19], v[102:103], v[56:57], v[18:19] op_sel_hi:[1,0,1]
	v_pk_fma_f32 v[16:17], v[100:101], v[56:57], v[16:17] op_sel:[0,1,0]
	v_pk_fma_f32 v[14:15], v[102:103], v[56:57], v[14:15] op_sel:[0,1,0]
	v_pk_fma_f32 v[12:13], v[100:101], v[58:59], v[12:13] op_sel_hi:[1,0,1]
	v_pk_fma_f32 v[10:11], v[102:103], v[58:59], v[10:11] op_sel_hi:[1,0,1]
	v_add_u32_e32 v27, 0x5a00, v48
	ds_read2_b32 v[50:51], v27 offset1:1
	ds_read2_b32 v[52:53], v27 offset0:2 offset1:3
	ds_read2_b32 v[54:55], v27 offset0:4 offset1:5
	ds_read2_b32 v[56:57], v27 offset0:6 offset1:7
	ds_read_b32 v58, v27 offset:32
	s_waitcnt vmcnt(22) lgkmcnt(5)
	v_pk_fma_f32 v[46:47], v[104:105], v[200:201], v[46:47] op_sel_hi:[1,0,1]
	v_pk_fma_f32 v[44:45], v[106:107], v[200:201], v[44:45] op_sel_hi:[1,0,1]
	v_pk_fma_f32 v[42:43], v[104:105], v[200:201], v[42:43] op_sel:[0,1,0]
	v_pk_fma_f32 v[40:41], v[106:107], v[200:201], v[40:41] op_sel:[0,1,0]
	v_pk_fma_f32 v[38:39], v[104:105], v[202:203], v[38:39] op_sel_hi:[1,0,1]
	v_pk_fma_f32 v[36:37], v[106:107], v[202:203], v[36:37] op_sel_hi:[1,0,1]
	v_pk_fma_f32 v[34:35], v[104:105], v[202:203], v[34:35] op_sel:[0,1,0]
	v_pk_fma_f32 v[32:33], v[106:107], v[202:203], v[32:33] op_sel:[0,1,0]
	v_pk_fma_f32 v[30:31], v[104:105], v[204:205], v[30:31] op_sel_hi:[1,0,1]
	v_pk_fma_f32 v[28:29], v[106:107], v[204:205], v[28:29] op_sel_hi:[1,0,1]
	v_pk_fma_f32 v[24:25], v[104:105], v[204:205], v[24:25] op_sel:[0,1,0]
	v_pk_fma_f32 v[22:23], v[106:107], v[204:205], v[22:23] op_sel:[0,1,0]
	v_pk_fma_f32 v[20:21], v[104:105], v[206:207], v[20:21] op_sel_hi:[1,0,1]
	v_pk_fma_f32 v[18:19], v[106:107], v[206:207], v[18:19] op_sel_hi:[1,0,1]
	v_pk_fma_f32 v[16:17], v[104:105], v[206:207], v[16:17] op_sel:[0,1,0]
	v_pk_fma_f32 v[14:15], v[106:107], v[206:207], v[14:15] op_sel:[0,1,0]
	v_pk_fma_f32 v[12:13], v[104:105], v[208:209], v[12:13] op_sel_hi:[1,0,1]
	v_pk_fma_f32 v[10:11], v[106:107], v[208:209], v[10:11] op_sel_hi:[1,0,1]
	v_add_u32_e32 v27, 0x6300, v48
	ds_read2_b32 v[200:201], v27 offset1:1
	ds_read2_b32 v[202:203], v27 offset0:2 offset1:3
	ds_read2_b32 v[204:205], v27 offset0:4 offset1:5
	ds_read2_b32 v[206:207], v27 offset0:6 offset1:7
	ds_read_b32 v208, v27 offset:32
	s_waitcnt vmcnt(21) lgkmcnt(5)
	v_pk_fma_f32 v[46:47], v[108:109], v[50:51], v[46:47] op_sel_hi:[1,0,1]
	v_pk_fma_f32 v[44:45], v[110:111], v[50:51], v[44:45] op_sel_hi:[1,0,1]
	v_pk_fma_f32 v[42:43], v[108:109], v[50:51], v[42:43] op_sel:[0,1,0]
	v_pk_fma_f32 v[40:41], v[110:111], v[50:51], v[40:41] op_sel:[0,1,0]
	v_pk_fma_f32 v[38:39], v[108:109], v[52:53], v[38:39] op_sel_hi:[1,0,1]
	v_pk_fma_f32 v[36:37], v[110:111], v[52:53], v[36:37] op_sel_hi:[1,0,1]
	v_pk_fma_f32 v[34:35], v[108:109], v[52:53], v[34:35] op_sel:[0,1,0]
	v_pk_fma_f32 v[32:33], v[110:111], v[52:53], v[32:33] op_sel:[0,1,0]
	v_pk_fma_f32 v[30:31], v[108:109], v[54:55], v[30:31] op_sel_hi:[1,0,1]
	v_pk_fma_f32 v[28:29], v[110:111], v[54:55], v[28:29] op_sel_hi:[1,0,1]
	v_pk_fma_f32 v[24:25], v[108:109], v[54:55], v[24:25] op_sel:[0,1,0]
	v_pk_fma_f32 v[22:23], v[110:111], v[54:55], v[22:23] op_sel:[0,1,0]
	v_pk_fma_f32 v[20:21], v[108:109], v[56:57], v[20:21] op_sel_hi:[1,0,1]
	v_pk_fma_f32 v[18:19], v[110:111], v[56:57], v[18:19] op_sel_hi:[1,0,1]
	v_pk_fma_f32 v[16:17], v[108:109], v[56:57], v[16:17] op_sel:[0,1,0]
	v_pk_fma_f32 v[14:15], v[110:111], v[56:57], v[14:15] op_sel:[0,1,0]
	v_pk_fma_f32 v[12:13], v[108:109], v[58:59], v[12:13] op_sel_hi:[1,0,1]
	v_pk_fma_f32 v[10:11], v[110:111], v[58:59], v[10:11] op_sel_hi:[1,0,1]
	v_add_u32_e32 v27, 0x6c00, v48
	ds_read2_b32 v[50:51], v27 offset1:1
	ds_read2_b32 v[52:53], v27 offset0:2 offset1:3
	ds_read2_b32 v[54:55], v27 offset0:4 offset1:5
	ds_read2_b32 v[56:57], v27 offset0:6 offset1:7
	ds_read_b32 v58, v27 offset:32
	s_waitcnt vmcnt(20) lgkmcnt(5)
	v_pk_fma_f32 v[46:47], v[112:113], v[200:201], v[46:47] op_sel_hi:[1,0,1]
	v_pk_fma_f32 v[44:45], v[114:115], v[200:201], v[44:45] op_sel_hi:[1,0,1]
	v_pk_fma_f32 v[42:43], v[112:113], v[200:201], v[42:43] op_sel:[0,1,0]
	v_pk_fma_f32 v[40:41], v[114:115], v[200:201], v[40:41] op_sel:[0,1,0]
	v_pk_fma_f32 v[38:39], v[112:113], v[202:203], v[38:39] op_sel_hi:[1,0,1]
	v_pk_fma_f32 v[36:37], v[114:115], v[202:203], v[36:37] op_sel_hi:[1,0,1]
	v_pk_fma_f32 v[34:35], v[112:113], v[202:203], v[34:35] op_sel:[0,1,0]
	v_pk_fma_f32 v[32:33], v[114:115], v[202:203], v[32:33] op_sel:[0,1,0]
	v_pk_fma_f32 v[30:31], v[112:113], v[204:205], v[30:31] op_sel_hi:[1,0,1]
	v_pk_fma_f32 v[28:29], v[114:115], v[204:205], v[28:29] op_sel_hi:[1,0,1]
	v_pk_fma_f32 v[24:25], v[112:113], v[204:205], v[24:25] op_sel:[0,1,0]
	v_pk_fma_f32 v[22:23], v[114:115], v[204:205], v[22:23] op_sel:[0,1,0]
	v_pk_fma_f32 v[20:21], v[112:113], v[206:207], v[20:21] op_sel_hi:[1,0,1]
	v_pk_fma_f32 v[18:19], v[114:115], v[206:207], v[18:19] op_sel_hi:[1,0,1]
	v_pk_fma_f32 v[16:17], v[112:113], v[206:207], v[16:17] op_sel:[0,1,0]
	v_pk_fma_f32 v[14:15], v[114:115], v[206:207], v[14:15] op_sel:[0,1,0]
	v_pk_fma_f32 v[12:13], v[112:113], v[208:209], v[12:13] op_sel_hi:[1,0,1]
	v_pk_fma_f32 v[10:11], v[114:115], v[208:209], v[10:11] op_sel_hi:[1,0,1]
	v_add_u32_e32 v27, 0x7500, v48
	ds_read2_b32 v[200:201], v27 offset1:1
	ds_read2_b32 v[202:203], v27 offset0:2 offset1:3
	ds_read2_b32 v[204:205], v27 offset0:4 offset1:5
	ds_read2_b32 v[206:207], v27 offset0:6 offset1:7
	ds_read_b32 v208, v27 offset:32
	s_waitcnt vmcnt(19) lgkmcnt(5)
; __device__ __forceinline__ void ada_phase(LAS unsigned char* lds, const float* c, const float* c_ctx, const float* ada_w, const float* ada_b, float* mods, int G, int bid, int tid, int item0, int item1) {
;     ...
; #pragma unroll 16
;         for (int i = 0; i < 32; ++i) { const int k = ks + 64 * i; const f32x4 w = *(const f32x4*)(wp + (size_t)k * MODW);
; #pragma unroll
;             for (int r = 0; r < 9; ++r) acc[r] += w * sT[k * 9 + r]; }
	v_pk_fma_f32 v[46:47], v[116:117], v[50:51], v[46:47] op_sel_hi:[1,0,1]
	v_pk_fma_f32 v[44:45], v[118:119], v[50:51], v[44:45] op_sel_hi:[1,0,1]
	v_pk_fma_f32 v[42:43], v[116:117], v[50:51], v[42:43] op_sel:[0,1,0]
	v_pk_fma_f32 v[40:41], v[118:119], v[50:51], v[40:41] op_sel:[0,1,0]
	v_pk_fma_f32 v[38:39], v[116:117], v[52:53], v[38:39] op_sel_hi:[1,0,1]
	v_pk_fma_f32 v[36:37], v[118:119], v[52:53], v[36:37] op_sel_hi:[1,0,1]
	v_pk_fma_f32 v[34:35], v[116:117], v[52:53], v[34:35] op_sel:[0,1,0]
	v_pk_fma_f32 v[32:33], v[118:119], v[52:53], v[32:33] op_sel:[0,1,0]
	v_pk_fma_f32 v[30:31], v[116:117], v[54:55], v[30:31] op_sel_hi:[1,0,1]
	v_pk_fma_f32 v[28:29], v[118:119], v[54:55], v[28:29] op_sel_hi:[1,0,1]
	v_pk_fma_f32 v[24:25], v[116:117], v[54:55], v[24:25] op_sel:[0,1,0]
	v_pk_fma_f32 v[22:23], v[118:119], v[54:55], v[22:23] op_sel:[0,1,0]
	v_pk_fma_f32 v[20:21], v[116:117], v[56:57], v[20:21] op_sel_hi:[1,0,1]
	v_pk_fma_f32 v[18:19], v[118:119], v[56:57], v[18:19] op_sel_hi:[1,0,1]
	v_pk_fma_f32 v[16:17], v[116:117], v[56:57], v[16:17] op_sel:[0,1,0]
	v_pk_fma_f32 v[14:15], v[118:119], v[56:57], v[14:15] op_sel:[0,1,0]
	v_pk_fma_f32 v[12:13], v[116:117], v[58:59], v[12:13] op_sel_hi:[1,0,1]
	v_pk_fma_f32 v[10:11], v[118:119], v[58:59], v[10:11] op_sel_hi:[1,0,1]
	v_add_u32_e32 v27, 0x7e00, v48
	ds_read2_b32 v[50:51], v27 offset1:1
	ds_read2_b32 v[52:53], v27 offset0:2 offset1:3
	ds_read2_b32 v[54:55], v27 offset0:4 offset1:5
	ds_read2_b32 v[56:57], v27 offset0:6 offset1:7
	ds_read_b32 v58, v27 offset:32
	s_waitcnt vmcnt(18) lgkmcnt(5)
	v_pk_fma_f32 v[46:47], v[120:121], v[200:201], v[46:47] op_sel_hi:[1,0,1]
	v_pk_fma_f32 v[44:45], v[122:123], v[200:201], v[44:45] op_sel_hi:[1,0,1]
	v_pk_fma_f32 v[42:43], v[120:121], v[200:201], v[42:43] op_sel:[0,1,0]
	v_pk_fma_f32 v[40:41], v[122:123], v[200:201], v[40:41] op_sel:[0,1,0]
	v_pk_fma_f32 v[38:39], v[120:121], v[202:203], v[38:39] op_sel_hi:[1,0,1]
	v_pk_fma_f32 v[36:37], v[122:123], v[202:203], v[36:37] op_sel_hi:[1,0,1]
	v_pk_fma_f32 v[34:35], v[120:121], v[202:203], v[34:35] op_sel:[0,1,0]
	v_pk_fma_f32 v[32:33], v[122:123], v[202:203], v[32:33] op_sel:[0,1,0]
	v_pk_fma_f32 v[30:31], v[120:121], v[204:205], v[30:31] op_sel_hi:[1,0,1]
	v_pk_fma_f32 v[28:29], v[122:123], v[204:205], v[28:29] op_sel_hi:[1,0,1]
	v_pk_fma_f32 v[24:25], v[120:121], v[204:205], v[24:25] op_sel:[0,1,0]
	v_pk_fma_f32 v[22:23], v[122:123], v[204:205], v[22:23] op_sel:[0,1,0]
	v_pk_fma_f32 v[20:21], v[120:121], v[206:207], v[20:21] op_sel_hi:[1,0,1]
	v_pk_fma_f32 v[18:19], v[122:123], v[206:207], v[18:19] op_sel_hi:[1,0,1]
	v_pk_fma_f32 v[16:17], v[120:121], v[206:207], v[16:17] op_sel:[0,1,0]
	v_pk_fma_f32 v[14:15], v[122:123], v[206:207], v[14:15] op_sel:[0,1,0]
	v_pk_fma_f32 v[12:13], v[120:121], v[208:209], v[12:13] op_sel_hi:[1,0,1]
	v_pk_fma_f32 v[10:11], v[122:123], v[208:209], v[10:11] op_sel_hi:[1,0,1]
	v_add_u32_e32 v27, 0x8700, v48
	ds_read2_b32 v[200:201], v27 offset1:1
	ds_read2_b32 v[202:203], v27 offset0:2 offset1:3
	ds_read2_b32 v[204:205], v27 offset0:4 offset1:5
	ds_read2_b32 v[206:207], v27 offset0:6 offset1:7
	ds_read_b32 v208, v27 offset:32
	s_waitcnt vmcnt(17) lgkmcnt(5)
	v_pk_fma_f32 v[46:47], v[124:125], v[50:51], v[46:47] op_sel_hi:[1,0,1]
	v_pk_fma_f32 v[44:45], v[126:127], v[50:51], v[44:45] op_sel_hi:[1,0,1]
	v_pk_fma_f32 v[42:43], v[124:125], v[50:51], v[42:43] op_sel:[0,1,0]
	v_pk_fma_f32 v[40:41], v[126:127], v[50:51], v[40:41] op_sel:[0,1,0]
	v_pk_fma_f32 v[38:39], v[124:125], v[52:53], v[38:39] op_sel_hi:[1,0,1]
	v_pk_fma_f32 v[36:37], v[126:127], v[52:53], v[36:37] op_sel_hi:[1,0,1]
	v_pk_fma_f32 v[34:35], v[124:125], v[52:53], v[34:35] op_sel:[0,1,0]
	v_pk_fma_f32 v[32:33], v[126:127], v[52:53], v[32:33] op_sel:[0,1,0]
	v_pk_fma_f32 v[30:31], v[124:125], v[54:55], v[30:31] op_sel_hi:[1,0,1]
	v_pk_fma_f32 v[28:29], v[126:127], v[54:55], v[28:29] op_sel_hi:[1,0,1]
	v_pk_fma_f32 v[24:25], v[124:125], v[54:55], v[24:25] op_sel:[0,1,0]
	v_pk_fma_f32 v[22:23], v[126:127], v[54:55], v[22:23] op_sel:[0,1,0]
	v_pk_fma_f32 v[20:21], v[124:125], v[56:57], v[20:21] op_sel_hi:[1,0,1]
	v_pk_fma_f32 v[18:19], v[126:127], v[56:57], v[18:19] op_sel_hi:[1,0,1]
	v_pk_fma_f32 v[16:17], v[124:125], v[56:57], v[16:17] op_sel:[0,1,0]
	v_pk_fma_f32 v[14:15], v[126:127], v[56:57], v[14:15] op_sel:[0,1,0]
	v_pk_fma_f32 v[12:13], v[124:125], v[58:59], v[12:13] op_sel_hi:[1,0,1]
	v_pk_fma_f32 v[10:11], v[126:127], v[58:59], v[10:11] op_sel_hi:[1,0,1]
	v_add_u32_e32 v27, 0x9000, v48
	ds_read2_b32 v[50:51], v27 offset1:1
	ds_read2_b32 v[52:53], v27 offset0:2 offset1:3
	ds_read2_b32 v[54:55], v27 offset0:4 offset1:5
	ds_read2_b32 v[56:57], v27 offset0:6 offset1:7
	ds_read_b32 v58, v27 offset:32
	s_waitcnt vmcnt(16) lgkmcnt(5)
	v_pk_fma_f32 v[46:47], v[128:129], v[200:201], v[46:47] op_sel_hi:[1,0,1]
	v_pk_fma_f32 v[44:45], v[130:131], v[200:201], v[44:45] op_sel_hi:[1,0,1]
	v_pk_fma_f32 v[42:43], v[128:129], v[200:201], v[42:43] op_sel:[0,1,0]
	v_pk_fma_f32 v[40:41], v[130:131], v[200:201], v[40:41] op_sel:[0,1,0]
	v_pk_fma_f32 v[38:39], v[128:129], v[202:203], v[38:39] op_sel_hi:[1,0,1]
	v_pk_fma_f32 v[36:37], v[130:131], v[202:203], v[36:37] op_sel_hi:[1,0,1]
	v_pk_fma_f32 v[34:35], v[128:129], v[202:203], v[34:35] op_sel:[0,1,0]
	v_pk_fma_f32 v[32:33], v[130:131], v[202:203], v[32:33] op_sel:[0,1,0]
	v_pk_fma_f32 v[30:31], v[128:129], v[204:205], v[30:31] op_sel_hi:[1,0,1]
	v_pk_fma_f32 v[28:29], v[130:131], v[204:205], v[28:29] op_sel_hi:[1,0,1]
	v_pk_fma_f32 v[24:25], v[128:129], v[204:205], v[24:25] op_sel:[0,1,0]
	v_pk_fma_f32 v[22:23], v[130:131], v[204:205], v[22:23] op_sel:[0,1,0]
	v_pk_fma_f32 v[20:21], v[128:129], v[206:207], v[20:21] op_sel_hi:[1,0,1]
	v_pk_fma_f32 v[18:19], v[130:131], v[206:207], v[18:19] op_sel_hi:[1,0,1]
	v_pk_fma_f32 v[16:17], v[128:129], v[206:207], v[16:17] op_sel:[0,1,0]
	v_pk_fma_f32 v[14:15], v[130:131], v[206:207], v[14:15] op_sel:[0,1,0]
	v_pk_fma_f32 v[12:13], v[128:129], v[208:209], v[12:13] op_sel_hi:[1,0,1]
	v_pk_fma_f32 v[10:11], v[130:131], v[208:209], v[10:11] op_sel_hi:[1,0,1]
	v_add_u32_e32 v27, 0x9900, v48
	ds_read2_b32 v[200:201], v27 offset1:1
	ds_read2_b32 v[202:203], v27 offset0:2 offset1:3
	ds_read2_b32 v[204:205], v27 offset0:4 offset1:5
	ds_read2_b32 v[206:207], v27 offset0:6 offset1:7
	ds_read_b32 v208, v27 offset:32
	s_waitcnt vmcnt(15) lgkmcnt(5)
; __device__ __forceinline__ void ada_phase(LAS unsigned char* lds, const float* c, const float* c_ctx, const float* ada_w, const float* ada_b, float* mods, int G, int bid, int tid, int item0, int item1) {
;     ...
; #pragma unroll 16
;         for (int i = 0; i < 32; ++i) { const int k = ks + 64 * i; const f32x4 w = *(const f32x4*)(wp + (size_t)k * MODW);
; #pragma unroll
;             for (int r = 0; r < 9; ++r) acc[r] += w * sT[k * 9 + r]; }
	v_pk_fma_f32 v[46:47], v[132:133], v[50:51], v[46:47] op_sel_hi:[1,0,1]
	v_pk_fma_f32 v[44:45], v[134:135], v[50:51], v[44:45] op_sel_hi:[1,0,1]
	v_pk_fma_f32 v[42:43], v[132:133], v[50:51], v[42:43] op_sel:[0,1,0]
	v_pk_fma_f32 v[40:41], v[134:135], v[50:51], v[40:41] op_sel:[0,1,0]
	v_pk_fma_f32 v[38:39], v[132:133], v[52:53], v[38:39] op_sel_hi:[1,0,1]
	v_pk_fma_f32 v[36:37], v[134:135], v[52:53], v[36:37] op_sel_hi:[1,0,1]
	v_pk_fma_f32 v[34:35], v[132:133], v[52:53], v[34:35] op_sel:[0,1,0]
	v_pk_fma_f32 v[32:33], v[134:135], v[52:53], v[32:33] op_sel:[0,1,0]
	v_pk_fma_f32 v[30:31], v[132:133], v[54:55], v[30:31] op_sel_hi:[1,0,1]
	v_pk_fma_f32 v[28:29], v[134:135], v[54:55], v[28:29] op_sel_hi:[1,0,1]
	v_pk_fma_f32 v[24:25], v[132:133], v[54:55], v[24:25] op_sel:[0,1,0]
	v_pk_fma_f32 v[22:23], v[134:135], v[54:55], v[22:23] op_sel:[0,1,0]
	v_pk_fma_f32 v[20:21], v[132:133], v[56:57], v[20:21] op_sel_hi:[1,0,1]
	v_pk_fma_f32 v[18:19], v[134:135], v[56:57], v[18:19] op_sel_hi:[1,0,1]
	v_pk_fma_f32 v[16:17], v[132:133], v[56:57], v[16:17] op_sel:[0,1,0]
	v_pk_fma_f32 v[14:15], v[134:135], v[56:57], v[14:15] op_sel:[0,1,0]
	v_pk_fma_f32 v[12:13], v[132:133], v[58:59], v[12:13] op_sel_hi:[1,0,1]
	v_pk_fma_f32 v[10:11], v[134:135], v[58:59], v[10:11] op_sel_hi:[1,0,1]
	v_add_u32_e32 v27, 0xa200, v48
	ds_read2_b32 v[50:51], v27 offset1:1
	ds_read2_b32 v[52:53], v27 offset0:2 offset1:3
	ds_read2_b32 v[54:55], v27 offset0:4 offset1:5
	ds_read2_b32 v[56:57], v27 offset0:6 offset1:7
	ds_read_b32 v58, v27 offset:32
	s_waitcnt vmcnt(14) lgkmcnt(5)
	v_pk_fma_f32 v[46:47], v[136:137], v[200:201], v[46:47] op_sel_hi:[1,0,1]
	v_pk_fma_f32 v[44:45], v[138:139], v[200:201], v[44:45] op_sel_hi:[1,0,1]
	v_pk_fma_f32 v[42:43], v[136:137], v[200:201], v[42:43] op_sel:[0,1,0]
	v_pk_fma_f32 v[40:41], v[138:139], v[200:201], v[40:41] op_sel:[0,1,0]
	v_pk_fma_f32 v[38:39], v[136:137], v[202:203], v[38:39] op_sel_hi:[1,0,1]
	v_pk_fma_f32 v[36:37], v[138:139], v[202:203], v[36:37] op_sel_hi:[1,0,1]
	v_pk_fma_f32 v[34:35], v[136:137], v[202:203], v[34:35] op_sel:[0,1,0]
	v_pk_fma_f32 v[32:33], v[138:139], v[202:203], v[32:33] op_sel:[0,1,0]
	v_pk_fma_f32 v[30:31], v[136:137], v[204:205], v[30:31] op_sel_hi:[1,0,1]
	v_pk_fma_f32 v[28:29], v[138:139], v[204:205], v[28:29] op_sel_hi:[1,0,1]
	v_pk_fma_f32 v[24:25], v[136:137], v[204:205], v[24:25] op_sel:[0,1,0]
	v_pk_fma_f32 v[22:23], v[138:139], v[204:205], v[22:23] op_sel:[0,1,0]
	v_pk_fma_f32 v[20:21], v[136:137], v[206:207], v[20:21] op_sel_hi:[1,0,1]
	v_pk_fma_f32 v[18:19], v[138:139], v[206:207], v[18:19] op_sel_hi:[1,0,1]
	v_pk_fma_f32 v[16:17], v[136:137], v[206:207], v[16:17] op_sel:[0,1,0]
	v_pk_fma_f32 v[14:15], v[138:139], v[206:207], v[14:15] op_sel:[0,1,0]
	v_pk_fma_f32 v[12:13], v[136:137], v[208:209], v[12:13] op_sel_hi:[1,0,1]
	v_pk_fma_f32 v[10:11], v[138:139], v[208:209], v[10:11] op_sel_hi:[1,0,1]
	v_add_u32_e32 v27, 0xab00, v48
	ds_read2_b32 v[200:201], v27 offset1:1
	ds_read2_b32 v[202:203], v27 offset0:2 offset1:3
	ds_read2_b32 v[204:205], v27 offset0:4 offset1:5
	ds_read2_b32 v[206:207], v27 offset0:6 offset1:7
	ds_read_b32 v208, v27 offset:32
	s_waitcnt vmcnt(13) lgkmcnt(5)
	v_pk_fma_f32 v[46:47], v[140:141], v[50:51], v[46:47] op_sel_hi:[1,0,1]
	v_pk_fma_f32 v[44:45], v[142:143], v[50:51], v[44:45] op_sel_hi:[1,0,1]
	v_pk_fma_f32 v[42:43], v[140:141], v[50:51], v[42:43] op_sel:[0,1,0]
	v_pk_fma_f32 v[40:41], v[142:143], v[50:51], v[40:41] op_sel:[0,1,0]
	v_pk_fma_f32 v[38:39], v[140:141], v[52:53], v[38:39] op_sel_hi:[1,0,1]
	v_pk_fma_f32 v[36:37], v[142:143], v[52:53], v[36:37] op_sel_hi:[1,0,1]
	v_pk_fma_f32 v[34:35], v[140:141], v[52:53], v[34:35] op_sel:[0,1,0]
	v_pk_fma_f32 v[32:33], v[142:143], v[52:53], v[32:33] op_sel:[0,1,0]
	v_pk_fma_f32 v[30:31], v[140:141], v[54:55], v[30:31] op_sel_hi:[1,0,1]
	v_pk_fma_f32 v[28:29], v[142:143], v[54:55], v[28:29] op_sel_hi:[1,0,1]
	v_pk_fma_f32 v[24:25], v[140:141], v[54:55], v[24:25] op_sel:[0,1,0]
	v_pk_fma_f32 v[22:23], v[142:143], v[54:55], v[22:23] op_sel:[0,1,0]
	v_pk_fma_f32 v[20:21], v[140:141], v[56:57], v[20:21] op_sel_hi:[1,0,1]
	v_pk_fma_f32 v[18:19], v[142:143], v[56:57], v[18:19] op_sel_hi:[1,0,1]
	v_pk_fma_f32 v[16:17], v[140:141], v[56:57], v[16:17] op_sel:[0,1,0]
	v_pk_fma_f32 v[14:15], v[142:143], v[56:57], v[14:15] op_sel:[0,1,0]
	v_pk_fma_f32 v[12:13], v[140:141], v[58:59], v[12:13] op_sel_hi:[1,0,1]
	v_pk_fma_f32 v[10:11], v[142:143], v[58:59], v[10:11] op_sel_hi:[1,0,1]
	v_add_u32_e32 v27, 0xb400, v48
	ds_read2_b32 v[50:51], v27 offset1:1
	ds_read2_b32 v[52:53], v27 offset0:2 offset1:3
	ds_read2_b32 v[54:55], v27 offset0:4 offset1:5
	ds_read2_b32 v[56:57], v27 offset0:6 offset1:7
	ds_read_b32 v58, v27 offset:32
	s_waitcnt vmcnt(12) lgkmcnt(5)
	v_pk_fma_f32 v[46:47], v[144:145], v[200:201], v[46:47] op_sel_hi:[1,0,1]
	v_pk_fma_f32 v[44:45], v[146:147], v[200:201], v[44:45] op_sel_hi:[1,0,1]
	v_pk_fma_f32 v[42:43], v[144:145], v[200:201], v[42:43] op_sel:[0,1,0]
	v_pk_fma_f32 v[40:41], v[146:147], v[200:201], v[40:41] op_sel:[0,1,0]
	v_pk_fma_f32 v[38:39], v[144:145], v[202:203], v[38:39] op_sel_hi:[1,0,1]
	v_pk_fma_f32 v[36:37], v[146:147], v[202:203], v[36:37] op_sel_hi:[1,0,1]
	v_pk_fma_f32 v[34:35], v[144:145], v[202:203], v[34:35] op_sel:[0,1,0]
	v_pk_fma_f32 v[32:33], v[146:147], v[202:203], v[32:33] op_sel:[0,1,0]
	v_pk_fma_f32 v[30:31], v[144:145], v[204:205], v[30:31] op_sel_hi:[1,0,1]
	v_pk_fma_f32 v[28:29], v[146:147], v[204:205], v[28:29] op_sel_hi:[1,0,1]
	v_pk_fma_f32 v[24:25], v[144:145], v[204:205], v[24:25] op_sel:[0,1,0]
	v_pk_fma_f32 v[22:23], v[146:147], v[204:205], v[22:23] op_sel:[0,1,0]
	v_pk_fma_f32 v[20:21], v[144:145], v[206:207], v[20:21] op_sel_hi:[1,0,1]
	v_pk_fma_f32 v[18:19], v[146:147], v[206:207], v[18:19] op_sel_hi:[1,0,1]
	v_pk_fma_f32 v[16:17], v[144:145], v[206:207], v[16:17] op_sel:[0,1,0]
	v_pk_fma_f32 v[14:15], v[146:147], v[206:207], v[14:15] op_sel:[0,1,0]
	v_pk_fma_f32 v[12:13], v[144:145], v[208:209], v[12:13] op_sel_hi:[1,0,1]
	v_pk_fma_f32 v[10:11], v[146:147], v[208:209], v[10:11] op_sel_hi:[1,0,1]
	v_add_u32_e32 v27, 0xbd00, v48
	ds_read2_b32 v[200:201], v27 offset1:1
	ds_read2_b32 v[202:203], v27 offset0:2 offset1:3
	ds_read2_b32 v[204:205], v27 offset0:4 offset1:5
	ds_read2_b32 v[206:207], v27 offset0:6 offset1:7
	ds_read_b32 v208, v27 offset:32
	s_waitcnt vmcnt(11) lgkmcnt(5)
; __device__ __forceinline__ void ada_phase(LAS unsigned char* lds, const float* c, const float* c_ctx, const float* ada_w, const float* ada_b, float* mods, int G, int bid, int tid, int item0, int item1) {
;     ...
; #pragma unroll 16
;         for (int i = 0; i < 32; ++i) { const int k = ks + 64 * i; const f32x4 w = *(const f32x4*)(wp + (size_t)k * MODW);
; #pragma unroll
;             for (int r = 0; r < 9; ++r) acc[r] += w * sT[k * 9 + r]; }
	v_pk_fma_f32 v[46:47], v[148:149], v[50:51], v[46:47] op_sel_hi:[1,0,1]
	v_pk_fma_f32 v[44:45], v[150:151], v[50:51], v[44:45] op_sel_hi:[1,0,1]
	v_pk_fma_f32 v[42:43], v[148:149], v[50:51], v[42:43] op_sel:[0,1,0]
	v_pk_fma_f32 v[40:41], v[150:151], v[50:51], v[40:41] op_sel:[0,1,0]
	v_pk_fma_f32 v[38:39], v[148:149], v[52:53], v[38:39] op_sel_hi:[1,0,1]
	v_pk_fma_f32 v[36:37], v[150:151], v[52:53], v[36:37] op_sel_hi:[1,0,1]
	v_pk_fma_f32 v[34:35], v[148:149], v[52:53], v[34:35] op_sel:[0,1,0]
	v_pk_fma_f32 v[32:33], v[150:151], v[52:53], v[32:33] op_sel:[0,1,0]
	v_pk_fma_f32 v[30:31], v[148:149], v[54:55], v[30:31] op_sel_hi:[1,0,1]
	v_pk_fma_f32 v[28:29], v[150:151], v[54:55], v[28:29] op_sel_hi:[1,0,1]
	v_pk_fma_f32 v[24:25], v[148:149], v[54:55], v[24:25] op_sel:[0,1,0]
	v_pk_fma_f32 v[22:23], v[150:151], v[54:55], v[22:23] op_sel:[0,1,0]
	v_pk_fma_f32 v[20:21], v[148:149], v[56:57], v[20:21] op_sel_hi:[1,0,1]
	v_pk_fma_f32 v[18:19], v[150:151], v[56:57], v[18:19] op_sel_hi:[1,0,1]
	v_pk_fma_f32 v[16:17], v[148:149], v[56:57], v[16:17] op_sel:[0,1,0]
	v_pk_fma_f32 v[14:15], v[150:151], v[56:57], v[14:15] op_sel:[0,1,0]
	v_pk_fma_f32 v[12:13], v[148:149], v[58:59], v[12:13] op_sel_hi:[1,0,1]
	v_pk_fma_f32 v[10:11], v[150:151], v[58:59], v[10:11] op_sel_hi:[1,0,1]
	v_add_u32_e32 v27, 0xc600, v48
	ds_read2_b32 v[50:51], v27 offset1:1
	ds_read2_b32 v[52:53], v27 offset0:2 offset1:3
	ds_read2_b32 v[54:55], v27 offset0:4 offset1:5
	ds_read2_b32 v[56:57], v27 offset0:6 offset1:7
	ds_read_b32 v58, v27 offset:32
	s_waitcnt vmcnt(10) lgkmcnt(5)
	v_pk_fma_f32 v[46:47], v[152:153], v[200:201], v[46:47] op_sel_hi:[1,0,1]
	v_pk_fma_f32 v[44:45], v[154:155], v[200:201], v[44:45] op_sel_hi:[1,0,1]
	v_pk_fma_f32 v[42:43], v[152:153], v[200:201], v[42:43] op_sel:[0,1,0]
	v_pk_fma_f32 v[40:41], v[154:155], v[200:201], v[40:41] op_sel:[0,1,0]
	v_pk_fma_f32 v[38:39], v[152:153], v[202:203], v[38:39] op_sel_hi:[1,0,1]
	v_pk_fma_f32 v[36:37], v[154:155], v[202:203], v[36:37] op_sel_hi:[1,0,1]
	v_pk_fma_f32 v[34:35], v[152:153], v[202:203], v[34:35] op_sel:[0,1,0]
	v_pk_fma_f32 v[32:33], v[154:155], v[202:203], v[32:33] op_sel:[0,1,0]
	v_pk_fma_f32 v[30:31], v[152:153], v[204:205], v[30:31] op_sel_hi:[1,0,1]
	v_pk_fma_f32 v[28:29], v[154:155], v[204:205], v[28:29] op_sel_hi:[1,0,1]
	v_pk_fma_f32 v[24:25], v[152:153], v[204:205], v[24:25] op_sel:[0,1,0]
	v_pk_fma_f32 v[22:23], v[154:155], v[204:205], v[22:23] op_sel:[0,1,0]
	v_pk_fma_f32 v[20:21], v[152:153], v[206:207], v[20:21] op_sel_hi:[1,0,1]
	v_pk_fma_f32 v[18:19], v[154:155], v[206:207], v[18:19] op_sel_hi:[1,0,1]
	v_pk_fma_f32 v[16:17], v[152:153], v[206:207], v[16:17] op_sel:[0,1,0]
	v_pk_fma_f32 v[14:15], v[154:155], v[206:207], v[14:15] op_sel:[0,1,0]
	v_pk_fma_f32 v[12:13], v[152:153], v[208:209], v[12:13] op_sel_hi:[1,0,1]
	v_pk_fma_f32 v[10:11], v[154:155], v[208:209], v[10:11] op_sel_hi:[1,0,1]
	v_add_u32_e32 v27, 0xcf00, v48
	ds_read2_b32 v[200:201], v27 offset1:1
	ds_read2_b32 v[202:203], v27 offset0:2 offset1:3
	ds_read2_b32 v[204:205], v27 offset0:4 offset1:5
	ds_read2_b32 v[206:207], v27 offset0:6 offset1:7
	ds_read_b32 v208, v27 offset:32
	s_waitcnt vmcnt(9) lgkmcnt(5)
	v_pk_fma_f32 v[46:47], v[156:157], v[50:51], v[46:47] op_sel_hi:[1,0,1]
	v_pk_fma_f32 v[44:45], v[158:159], v[50:51], v[44:45] op_sel_hi:[1,0,1]
	v_pk_fma_f32 v[42:43], v[156:157], v[50:51], v[42:43] op_sel:[0,1,0]
	v_pk_fma_f32 v[40:41], v[158:159], v[50:51], v[40:41] op_sel:[0,1,0]
	v_pk_fma_f32 v[38:39], v[156:157], v[52:53], v[38:39] op_sel_hi:[1,0,1]
	v_pk_fma_f32 v[36:37], v[158:159], v[52:53], v[36:37] op_sel_hi:[1,0,1]
	v_pk_fma_f32 v[34:35], v[156:157], v[52:53], v[34:35] op_sel:[0,1,0]
	v_pk_fma_f32 v[32:33], v[158:159], v[52:53], v[32:33] op_sel:[0,1,0]
	v_pk_fma_f32 v[30:31], v[156:157], v[54:55], v[30:31] op_sel_hi:[1,0,1]
	v_pk_fma_f32 v[28:29], v[158:159], v[54:55], v[28:29] op_sel_hi:[1,0,1]
	v_pk_fma_f32 v[24:25], v[156:157], v[54:55], v[24:25] op_sel:[0,1,0]
	v_pk_fma_f32 v[22:23], v[158:159], v[54:55], v[22:23] op_sel:[0,1,0]
	v_pk_fma_f32 v[20:21], v[156:157], v[56:57], v[20:21] op_sel_hi:[1,0,1]
	v_pk_fma_f32 v[18:19], v[158:159], v[56:57], v[18:19] op_sel_hi:[1,0,1]
	v_pk_fma_f32 v[16:17], v[156:157], v[56:57], v[16:17] op_sel:[0,1,0]
	v_pk_fma_f32 v[14:15], v[158:159], v[56:57], v[14:15] op_sel:[0,1,0]
	v_pk_fma_f32 v[12:13], v[156:157], v[58:59], v[12:13] op_sel_hi:[1,0,1]
	v_pk_fma_f32 v[10:11], v[158:159], v[58:59], v[10:11] op_sel_hi:[1,0,1]
	v_add_u32_e32 v27, 0xd800, v48
	ds_read2_b32 v[50:51], v27 offset1:1
	ds_read2_b32 v[52:53], v27 offset0:2 offset1:3
	ds_read2_b32 v[54:55], v27 offset0:4 offset1:5
	ds_read2_b32 v[56:57], v27 offset0:6 offset1:7
	ds_read_b32 v58, v27 offset:32
	s_waitcnt vmcnt(8) lgkmcnt(5)
	v_pk_fma_f32 v[46:47], v[160:161], v[200:201], v[46:47] op_sel_hi:[1,0,1]
	v_pk_fma_f32 v[44:45], v[162:163], v[200:201], v[44:45] op_sel_hi:[1,0,1]
	v_pk_fma_f32 v[42:43], v[160:161], v[200:201], v[42:43] op_sel:[0,1,0]
	v_pk_fma_f32 v[40:41], v[162:163], v[200:201], v[40:41] op_sel:[0,1,0]
	v_pk_fma_f32 v[38:39], v[160:161], v[202:203], v[38:39] op_sel_hi:[1,0,1]
	v_pk_fma_f32 v[36:37], v[162:163], v[202:203], v[36:37] op_sel_hi:[1,0,1]
	v_pk_fma_f32 v[34:35], v[160:161], v[202:203], v[34:35] op_sel:[0,1,0]
	v_pk_fma_f32 v[32:33], v[162:163], v[202:203], v[32:33] op_sel:[0,1,0]
	v_pk_fma_f32 v[30:31], v[160:161], v[204:205], v[30:31] op_sel_hi:[1,0,1]
	v_pk_fma_f32 v[28:29], v[162:163], v[204:205], v[28:29] op_sel_hi:[1,0,1]
	v_pk_fma_f32 v[24:25], v[160:161], v[204:205], v[24:25] op_sel:[0,1,0]
	v_pk_fma_f32 v[22:23], v[162:163], v[204:205], v[22:23] op_sel:[0,1,0]
	v_pk_fma_f32 v[20:21], v[160:161], v[206:207], v[20:21] op_sel_hi:[1,0,1]
	v_pk_fma_f32 v[18:19], v[162:163], v[206:207], v[18:19] op_sel_hi:[1,0,1]
	v_pk_fma_f32 v[16:17], v[160:161], v[206:207], v[16:17] op_sel:[0,1,0]
	v_pk_fma_f32 v[14:15], v[162:163], v[206:207], v[14:15] op_sel:[0,1,0]
	v_pk_fma_f32 v[12:13], v[160:161], v[208:209], v[12:13] op_sel_hi:[1,0,1]
	v_pk_fma_f32 v[10:11], v[162:163], v[208:209], v[10:11] op_sel_hi:[1,0,1]
	v_add_u32_e32 v27, 0xe100, v48
	ds_read2_b32 v[200:201], v27 offset1:1
	ds_read2_b32 v[202:203], v27 offset0:2 offset1:3
	ds_read2_b32 v[204:205], v27 offset0:4 offset1:5
	ds_read2_b32 v[206:207], v27 offset0:6 offset1:7
	ds_read_b32 v208, v27 offset:32
	s_waitcnt vmcnt(7) lgkmcnt(5)
; __device__ __forceinline__ void ada_phase(LAS unsigned char* lds, const float* c, const float* c_ctx, const float* ada_w, const float* ada_b, float* mods, int G, int bid, int tid, int item0, int item1) {
;     ...
; #pragma unroll 16
;         for (int i = 0; i < 32; ++i) { const int k = ks + 64 * i; const f32x4 w = *(const f32x4*)(wp + (size_t)k * MODW);
; #pragma unroll
;             for (int r = 0; r < 9; ++r) acc[r] += w * sT[k * 9 + r]; }
	v_pk_fma_f32 v[46:47], v[168:169], v[50:51], v[46:47] op_sel_hi:[1,0,1]
	v_pk_fma_f32 v[44:45], v[170:171], v[50:51], v[44:45] op_sel_hi:[1,0,1]
	v_pk_fma_f32 v[42:43], v[168:169], v[50:51], v[42:43] op_sel:[0,1,0]
	v_pk_fma_f32 v[40:41], v[170:171], v[50:51], v[40:41] op_sel:[0,1,0]
	v_pk_fma_f32 v[38:39], v[168:169], v[52:53], v[38:39] op_sel_hi:[1,0,1]
	v_pk_fma_f32 v[36:37], v[170:171], v[52:53], v[36:37] op_sel_hi:[1,0,1]
	v_pk_fma_f32 v[34:35], v[168:169], v[52:53], v[34:35] op_sel:[0,1,0]
	v_pk_fma_f32 v[32:33], v[170:171], v[52:53], v[32:33] op_sel:[0,1,0]
	v_pk_fma_f32 v[30:31], v[168:169], v[54:55], v[30:31] op_sel_hi:[1,0,1]
	v_pk_fma_f32 v[28:29], v[170:171], v[54:55], v[28:29] op_sel_hi:[1,0,1]
	v_pk_fma_f32 v[24:25], v[168:169], v[54:55], v[24:25] op_sel:[0,1,0]
	v_pk_fma_f32 v[22:23], v[170:171], v[54:55], v[22:23] op_sel:[0,1,0]
	v_pk_fma_f32 v[20:21], v[168:169], v[56:57], v[20:21] op_sel_hi:[1,0,1]
	v_pk_fma_f32 v[18:19], v[170:171], v[56:57], v[18:19] op_sel_hi:[1,0,1]
	v_pk_fma_f32 v[16:17], v[168:169], v[56:57], v[16:17] op_sel:[0,1,0]
	v_pk_fma_f32 v[14:15], v[170:171], v[56:57], v[14:15] op_sel:[0,1,0]
	v_pk_fma_f32 v[12:13], v[168:169], v[58:59], v[12:13] op_sel_hi:[1,0,1]
	v_pk_fma_f32 v[10:11], v[170:171], v[58:59], v[10:11] op_sel_hi:[1,0,1]
	v_add_u32_e32 v27, 0xea00, v48
	ds_read2_b32 v[50:51], v27 offset1:1
	ds_read2_b32 v[52:53], v27 offset0:2 offset1:3
	ds_read2_b32 v[54:55], v27 offset0:4 offset1:5
	ds_read2_b32 v[56:57], v27 offset0:6 offset1:7
	ds_read_b32 v58, v27 offset:32
	s_waitcnt vmcnt(6) lgkmcnt(5)
	v_pk_fma_f32 v[46:47], v[172:173], v[200:201], v[46:47] op_sel_hi:[1,0,1]
	v_pk_fma_f32 v[44:45], v[174:175], v[200:201], v[44:45] op_sel_hi:[1,0,1]
	v_pk_fma_f32 v[42:43], v[172:173], v[200:201], v[42:43] op_sel:[0,1,0]
	v_pk_fma_f32 v[40:41], v[174:175], v[200:201], v[40:41] op_sel:[0,1,0]
	v_pk_fma_f32 v[38:39], v[172:173], v[202:203], v[38:39] op_sel_hi:[1,0,1]
	v_pk_fma_f32 v[36:37], v[174:175], v[202:203], v[36:37] op_sel_hi:[1,0,1]
	v_pk_fma_f32 v[34:35], v[172:173], v[202:203], v[34:35] op_sel:[0,1,0]
	v_pk_fma_f32 v[32:33], v[174:175], v[202:203], v[32:33] op_sel:[0,1,0]
	v_pk_fma_f32 v[30:31], v[172:173], v[204:205], v[30:31] op_sel_hi:[1,0,1]
	v_pk_fma_f32 v[28:29], v[174:175], v[204:205], v[28:29] op_sel_hi:[1,0,1]
	v_pk_fma_f32 v[24:25], v[172:173], v[204:205], v[24:25] op_sel:[0,1,0]
	v_pk_fma_f32 v[22:23], v[174:175], v[204:205], v[22:23] op_sel:[0,1,0]
	v_pk_fma_f32 v[20:21], v[172:173], v[206:207], v[20:21] op_sel_hi:[1,0,1]
	v_pk_fma_f32 v[18:19], v[174:175], v[206:207], v[18:19] op_sel_hi:[1,0,1]
	v_pk_fma_f32 v[16:17], v[172:173], v[206:207], v[16:17] op_sel:[0,1,0]
	v_pk_fma_f32 v[14:15], v[174:175], v[206:207], v[14:15] op_sel:[0,1,0]
	v_pk_fma_f32 v[12:13], v[172:173], v[208:209], v[12:13] op_sel_hi:[1,0,1]
	v_pk_fma_f32 v[10:11], v[174:175], v[208:209], v[10:11] op_sel_hi:[1,0,1]
	v_add_u32_e32 v27, 0xf300, v48
	ds_read2_b32 v[200:201], v27 offset1:1
	ds_read2_b32 v[202:203], v27 offset0:2 offset1:3
	ds_read2_b32 v[204:205], v27 offset0:4 offset1:5
	ds_read2_b32 v[206:207], v27 offset0:6 offset1:7
	ds_read_b32 v208, v27 offset:32
	s_waitcnt vmcnt(5) lgkmcnt(5)
	v_pk_fma_f32 v[46:47], v[176:177], v[50:51], v[46:47] op_sel_hi:[1,0,1]
	v_pk_fma_f32 v[44:45], v[178:179], v[50:51], v[44:45] op_sel_hi:[1,0,1]
	v_pk_fma_f32 v[42:43], v[176:177], v[50:51], v[42:43] op_sel:[0,1,0]
	v_pk_fma_f32 v[40:41], v[178:179], v[50:51], v[40:41] op_sel:[0,1,0]
	v_pk_fma_f32 v[38:39], v[176:177], v[52:53], v[38:39] op_sel_hi:[1,0,1]
	v_pk_fma_f32 v[36:37], v[178:179], v[52:53], v[36:37] op_sel_hi:[1,0,1]
	v_pk_fma_f32 v[34:35], v[176:177], v[52:53], v[34:35] op_sel:[0,1,0]
	v_pk_fma_f32 v[32:33], v[178:179], v[52:53], v[32:33] op_sel:[0,1,0]
	v_pk_fma_f32 v[30:31], v[176:177], v[54:55], v[30:31] op_sel_hi:[1,0,1]
	v_pk_fma_f32 v[28:29], v[178:179], v[54:55], v[28:29] op_sel_hi:[1,0,1]
	v_pk_fma_f32 v[24:25], v[176:177], v[54:55], v[24:25] op_sel:[0,1,0]
	v_pk_fma_f32 v[22:23], v[178:179], v[54:55], v[22:23] op_sel:[0,1,0]
	v_pk_fma_f32 v[20:21], v[176:177], v[56:57], v[20:21] op_sel_hi:[1,0,1]
	v_pk_fma_f32 v[18:19], v[178:179], v[56:57], v[18:19] op_sel_hi:[1,0,1]
	v_pk_fma_f32 v[16:17], v[176:177], v[56:57], v[16:17] op_sel:[0,1,0]
	v_pk_fma_f32 v[14:15], v[178:179], v[56:57], v[14:15] op_sel:[0,1,0]
	v_pk_fma_f32 v[12:13], v[176:177], v[58:59], v[12:13] op_sel_hi:[1,0,1]
	v_pk_fma_f32 v[10:11], v[178:179], v[58:59], v[10:11] op_sel_hi:[1,0,1]
	v_add_u32_e32 v27, 0xfc00, v48
	ds_read2_b32 v[50:51], v27 offset1:1
	ds_read2_b32 v[52:53], v27 offset0:2 offset1:3
	ds_read2_b32 v[54:55], v27 offset0:4 offset1:5
	ds_read2_b32 v[56:57], v27 offset0:6 offset1:7
	ds_read_b32 v58, v27 offset:32
	s_waitcnt vmcnt(4) lgkmcnt(5)
	v_pk_fma_f32 v[46:47], v[180:181], v[200:201], v[46:47] op_sel_hi:[1,0,1]
	v_pk_fma_f32 v[44:45], v[182:183], v[200:201], v[44:45] op_sel_hi:[1,0,1]
	v_pk_fma_f32 v[42:43], v[180:181], v[200:201], v[42:43] op_sel:[0,1,0]
	v_pk_fma_f32 v[40:41], v[182:183], v[200:201], v[40:41] op_sel:[0,1,0]
	v_pk_fma_f32 v[38:39], v[180:181], v[202:203], v[38:39] op_sel_hi:[1,0,1]
	v_pk_fma_f32 v[36:37], v[182:183], v[202:203], v[36:37] op_sel_hi:[1,0,1]
	v_pk_fma_f32 v[34:35], v[180:181], v[202:203], v[34:35] op_sel:[0,1,0]
	v_pk_fma_f32 v[32:33], v[182:183], v[202:203], v[32:33] op_sel:[0,1,0]
	v_pk_fma_f32 v[30:31], v[180:181], v[204:205], v[30:31] op_sel_hi:[1,0,1]
	v_pk_fma_f32 v[28:29], v[182:183], v[204:205], v[28:29] op_sel_hi:[1,0,1]
	v_pk_fma_f32 v[24:25], v[180:181], v[204:205], v[24:25] op_sel:[0,1,0]
	v_pk_fma_f32 v[22:23], v[182:183], v[204:205], v[22:23] op_sel:[0,1,0]
	v_pk_fma_f32 v[20:21], v[180:181], v[206:207], v[20:21] op_sel_hi:[1,0,1]
	v_pk_fma_f32 v[18:19], v[182:183], v[206:207], v[18:19] op_sel_hi:[1,0,1]
	v_pk_fma_f32 v[16:17], v[180:181], v[206:207], v[16:17] op_sel:[0,1,0]
	v_pk_fma_f32 v[14:15], v[182:183], v[206:207], v[14:15] op_sel:[0,1,0]
	v_pk_fma_f32 v[12:13], v[180:181], v[208:209], v[12:13] op_sel_hi:[1,0,1]
	v_pk_fma_f32 v[10:11], v[182:183], v[208:209], v[10:11] op_sel_hi:[1,0,1]
	v_add_u32_e32 v27, 0x10500, v48
	ds_read2_b32 v[200:201], v27 offset1:1
	ds_read2_b32 v[202:203], v27 offset0:2 offset1:3
	ds_read2_b32 v[204:205], v27 offset0:4 offset1:5
	ds_read2_b32 v[206:207], v27 offset0:6 offset1:7
	ds_read_b32 v208, v27 offset:32
	s_waitcnt vmcnt(3) lgkmcnt(5)
; __device__ __forceinline__ void ada_phase(LAS unsigned char* lds, const float* c, const float* c_ctx, const float* ada_w, const float* ada_b, float* mods, int G, int bid, int tid, int item0, int item1) {
;     ...
; #pragma unroll 16
;         for (int i = 0; i < 32; ++i) { const int k = ks + 64 * i; const f32x4 w = *(const f32x4*)(wp + (size_t)k * MODW);
; #pragma unroll
;             for (int r = 0; r < 9; ++r) acc[r] += w * sT[k * 9 + r]; }
; #pragma unroll
;         for (int r = 0; r < 9; ++r)
; #pragma unroll
;             for (int e = 0; e < 4; ++e) { float v = acc[r][e]; v += __shfl_xor(v, 8); v += __shfl_xor(v, 16); v += __shfl_xor(v, 32); acc[r][e] = v; }
	v_pk_fma_f32 v[46:47], v[184:185], v[50:51], v[46:47] op_sel_hi:[1,0,1]
	v_pk_fma_f32 v[44:45], v[186:187], v[50:51], v[44:45] op_sel_hi:[1,0,1]
	v_pk_fma_f32 v[42:43], v[184:185], v[50:51], v[42:43] op_sel:[0,1,0]
	v_pk_fma_f32 v[40:41], v[186:187], v[50:51], v[40:41] op_sel:[0,1,0]
	v_pk_fma_f32 v[38:39], v[184:185], v[52:53], v[38:39] op_sel_hi:[1,0,1]
	v_pk_fma_f32 v[36:37], v[186:187], v[52:53], v[36:37] op_sel_hi:[1,0,1]
	v_pk_fma_f32 v[34:35], v[184:185], v[52:53], v[34:35] op_sel:[0,1,0]
	v_pk_fma_f32 v[32:33], v[186:187], v[52:53], v[32:33] op_sel:[0,1,0]
	v_pk_fma_f32 v[30:31], v[184:185], v[54:55], v[30:31] op_sel_hi:[1,0,1]
	v_pk_fma_f32 v[28:29], v[186:187], v[54:55], v[28:29] op_sel_hi:[1,0,1]
	v_pk_fma_f32 v[24:25], v[184:185], v[54:55], v[24:25] op_sel:[0,1,0]
	v_pk_fma_f32 v[22:23], v[186:187], v[54:55], v[22:23] op_sel:[0,1,0]
	v_pk_fma_f32 v[20:21], v[184:185], v[56:57], v[20:21] op_sel_hi:[1,0,1]
	v_pk_fma_f32 v[18:19], v[186:187], v[56:57], v[18:19] op_sel_hi:[1,0,1]
	v_pk_fma_f32 v[16:17], v[184:185], v[56:57], v[16:17] op_sel:[0,1,0]
	v_pk_fma_f32 v[14:15], v[186:187], v[56:57], v[14:15] op_sel:[0,1,0]
	v_pk_fma_f32 v[12:13], v[184:185], v[58:59], v[12:13] op_sel_hi:[1,0,1]
	v_pk_fma_f32 v[10:11], v[186:187], v[58:59], v[10:11] op_sel_hi:[1,0,1]
	v_add_u32_e32 v27, 0x10e00, v48
	ds_read2_b32 v[50:51], v27 offset1:1
	ds_read2_b32 v[52:53], v27 offset0:2 offset1:3
	ds_read2_b32 v[54:55], v27 offset0:4 offset1:5
	ds_read2_b32 v[56:57], v27 offset0:6 offset1:7
	ds_read_b32 v58, v27 offset:32
	s_waitcnt vmcnt(2) lgkmcnt(5)
	v_pk_fma_f32 v[46:47], v[188:189], v[200:201], v[46:47] op_sel_hi:[1,0,1]
	v_pk_fma_f32 v[44:45], v[190:191], v[200:201], v[44:45] op_sel_hi:[1,0,1]
	v_pk_fma_f32 v[42:43], v[188:189], v[200:201], v[42:43] op_sel:[0,1,0]
	v_pk_fma_f32 v[40:41], v[190:191], v[200:201], v[40:41] op_sel:[0,1,0]
	v_pk_fma_f32 v[38:39], v[188:189], v[202:203], v[38:39] op_sel_hi:[1,0,1]
	v_pk_fma_f32 v[36:37], v[190:191], v[202:203], v[36:37] op_sel_hi:[1,0,1]
	v_pk_fma_f32 v[34:35], v[188:189], v[202:203], v[34:35] op_sel:[0,1,0]
	v_pk_fma_f32 v[32:33], v[190:191], v[202:203], v[32:33] op_sel:[0,1,0]
	v_pk_fma_f32 v[30:31], v[188:189], v[204:205], v[30:31] op_sel_hi:[1,0,1]
	v_pk_fma_f32 v[28:29], v[190:191], v[204:205], v[28:29] op_sel_hi:[1,0,1]
	v_pk_fma_f32 v[24:25], v[188:189], v[204:205], v[24:25] op_sel:[0,1,0]
	v_pk_fma_f32 v[22:23], v[190:191], v[204:205], v[22:23] op_sel:[0,1,0]
	v_pk_fma_f32 v[20:21], v[188:189], v[206:207], v[20:21] op_sel_hi:[1,0,1]
	v_pk_fma_f32 v[18:19], v[190:191], v[206:207], v[18:19] op_sel_hi:[1,0,1]
	v_pk_fma_f32 v[16:17], v[188:189], v[206:207], v[16:17] op_sel:[0,1,0]
	v_pk_fma_f32 v[14:15], v[190:191], v[206:207], v[14:15] op_sel:[0,1,0]
	v_pk_fma_f32 v[12:13], v[188:189], v[208:209], v[12:13] op_sel_hi:[1,0,1]
	v_pk_fma_f32 v[10:11], v[190:191], v[208:209], v[10:11] op_sel_hi:[1,0,1]
	v_add_u32_e32 v27, 0x11700, v48
	ds_read2_b32 v[200:201], v27 offset1:1
	ds_read2_b32 v[202:203], v27 offset0:2 offset1:3
	ds_read2_b32 v[204:205], v27 offset0:4 offset1:5
	ds_read2_b32 v[206:207], v27 offset0:6 offset1:7
	ds_read_b32 v208, v27 offset:32
	s_waitcnt vmcnt(1) lgkmcnt(5)
	v_pk_fma_f32 v[46:47], v[192:193], v[50:51], v[46:47] op_sel_hi:[1,0,1]
	v_pk_fma_f32 v[44:45], v[194:195], v[50:51], v[44:45] op_sel_hi:[1,0,1]
	v_pk_fma_f32 v[42:43], v[192:193], v[50:51], v[42:43] op_sel:[0,1,0]
	v_pk_fma_f32 v[40:41], v[194:195], v[50:51], v[40:41] op_sel:[0,1,0]
	v_pk_fma_f32 v[38:39], v[192:193], v[52:53], v[38:39] op_sel_hi:[1,0,1]
	v_pk_fma_f32 v[36:37], v[194:195], v[52:53], v[36:37] op_sel_hi:[1,0,1]
	v_pk_fma_f32 v[34:35], v[192:193], v[52:53], v[34:35] op_sel:[0,1,0]
	v_pk_fma_f32 v[32:33], v[194:195], v[52:53], v[32:33] op_sel:[0,1,0]
	v_pk_fma_f32 v[30:31], v[192:193], v[54:55], v[30:31] op_sel_hi:[1,0,1]
	v_pk_fma_f32 v[28:29], v[194:195], v[54:55], v[28:29] op_sel_hi:[1,0,1]
	v_pk_fma_f32 v[24:25], v[192:193], v[54:55], v[24:25] op_sel:[0,1,0]
	v_pk_fma_f32 v[22:23], v[194:195], v[54:55], v[22:23] op_sel:[0,1,0]
	v_pk_fma_f32 v[20:21], v[192:193], v[56:57], v[20:21] op_sel_hi:[1,0,1]
	v_pk_fma_f32 v[18:19], v[194:195], v[56:57], v[18:19] op_sel_hi:[1,0,1]
	v_pk_fma_f32 v[16:17], v[192:193], v[56:57], v[16:17] op_sel:[0,1,0]
	v_pk_fma_f32 v[14:15], v[194:195], v[56:57], v[14:15] op_sel:[0,1,0]
	v_pk_fma_f32 v[12:13], v[192:193], v[58:59], v[12:13] op_sel_hi:[1,0,1]
	v_pk_fma_f32 v[10:11], v[194:195], v[58:59], v[10:11] op_sel_hi:[1,0,1]
	s_waitcnt vmcnt(0) lgkmcnt(0)
	v_pk_fma_f32 v[46:47], v[196:197], v[200:201], v[46:47] op_sel_hi:[1,0,1]
	v_pk_fma_f32 v[44:45], v[198:199], v[200:201], v[44:45] op_sel_hi:[1,0,1]
	v_pk_fma_f32 v[42:43], v[196:197], v[200:201], v[42:43] op_sel:[0,1,0]
	v_pk_fma_f32 v[40:41], v[198:199], v[200:201], v[40:41] op_sel:[0,1,0]
	v_pk_fma_f32 v[38:39], v[196:197], v[202:203], v[38:39] op_sel_hi:[1,0,1]
	v_pk_fma_f32 v[36:37], v[198:199], v[202:203], v[36:37] op_sel_hi:[1,0,1]
	v_pk_fma_f32 v[34:35], v[196:197], v[202:203], v[34:35] op_sel:[0,1,0]
	v_pk_fma_f32 v[32:33], v[198:199], v[202:203], v[32:33] op_sel:[0,1,0]
	v_pk_fma_f32 v[30:31], v[196:197], v[204:205], v[30:31] op_sel_hi:[1,0,1]
	v_pk_fma_f32 v[28:29], v[198:199], v[204:205], v[28:29] op_sel_hi:[1,0,1]
	v_pk_fma_f32 v[24:25], v[196:197], v[204:205], v[24:25] op_sel:[0,1,0]
	v_pk_fma_f32 v[22:23], v[198:199], v[204:205], v[22:23] op_sel:[0,1,0]
	v_pk_fma_f32 v[20:21], v[196:197], v[206:207], v[20:21] op_sel_hi:[1,0,1]
	v_pk_fma_f32 v[18:19], v[198:199], v[206:207], v[18:19] op_sel_hi:[1,0,1]
	v_pk_fma_f32 v[16:17], v[196:197], v[206:207], v[16:17] op_sel:[0,1,0]
	v_pk_fma_f32 v[14:15], v[198:199], v[206:207], v[14:15] op_sel:[0,1,0]
	v_pk_fma_f32 v[12:13], v[196:197], v[208:209], v[12:13] op_sel_hi:[1,0,1]
	v_pk_fma_f32 v[10:11], v[198:199], v[208:209], v[10:11] op_sel_hi:[1,0,1]
	ds_bpermute_b32 v56, v3, v34
	ds_bpermute_b32 v57, v3, v35
	ds_bpermute_b32 v58, v3, v32
	ds_bpermute_b32 v59, v3, v33
	ds_bpermute_b32 v26, v3, v44
	ds_bpermute_b32 v27, v3, v45
	s_waitcnt lgkmcnt(4)
; __device__ __forceinline__ void ada_phase(LAS unsigned char* lds, const float* c, const float* c_ctx, const float* ada_w, const float* ada_b, float* mods, int G, int bid, int tid, int item0, int item1) {
;     ...
; #pragma unroll
;         for (int r = 0; r < 9; ++r)
; #pragma unroll
;             for (int e = 0; e < 4; ++e) { float v = acc[r][e]; v += __shfl_xor(v, 8); v += __shfl_xor(v, 16); v += __shfl_xor(v, 32); acc[r][e] = v; }
;         if (lane < 8) {
; #pragma unroll
;             for (int r = 0; r < 9; ++r)
; #pragma unroll
;                 for (int e = 0; e < 4; ++e) red[(wave * 9 + r) * 32 + 4 * cgp + e] = acc[r][e];
;         }
	v_pk_add_f32 v[34:35], v[34:35], v[56:57]
	ds_bpermute_b32 v56, v80, v34
	s_waitcnt lgkmcnt(3)
	v_pk_add_f32 v[58:59], v[32:33], v[58:59]
	ds_bpermute_b32 v57, v80, v35
	ds_bpermute_b32 v60, v80, v58
	ds_bpermute_b32 v61, v80, v59
	ds_bpermute_b32 v62, v3, v28
	ds_bpermute_b32 v63, v3, v29
	s_waitcnt lgkmcnt(4)
	v_pk_add_f32 v[32:33], v[34:35], v[56:57]
	v_pk_add_f32 v[44:45], v[44:45], v[26:27]
	s_waitcnt lgkmcnt(2)
	v_pk_add_f32 v[56:57], v[58:59], v[60:61]
	ds_bpermute_b32 v60, v3, v30
	ds_bpermute_b32 v61, v3, v31
	ds_bpermute_b32 v52, v3, v38
	ds_bpermute_b32 v53, v3, v39
	s_waitcnt lgkmcnt(4)
	v_pk_add_f32 v[62:63], v[28:29], v[62:63]
	ds_bpermute_b32 v72, v3, v16
	s_waitcnt lgkmcnt(3)
	v_pk_add_f32 v[30:31], v[30:31], v[60:61]
	ds_bpermute_b32 v73, v3, v17
	ds_bpermute_b32 v50, v80, v44
	ds_bpermute_b32 v51, v80, v45
	ds_bpermute_b32 v60, v80, v30
	ds_bpermute_b32 v61, v80, v31
	ds_bpermute_b32 v64, v80, v62
	ds_bpermute_b32 v65, v80, v63
	ds_bpermute_b32 v66, v3, v24
	ds_bpermute_b32 v67, v3, v25
	s_waitcnt lgkmcnt(10)
	v_pk_add_f32 v[38:39], v[38:39], v[52:53]
	s_waitcnt lgkmcnt(8)
	v_pk_add_f32 v[16:17], v[16:17], v[72:73]
	ds_bpermute_b32 v8, v3, v46
	ds_bpermute_b32 v9, v3, v47
	ds_bpermute_b32 v48, v3, v42
	ds_bpermute_b32 v49, v3, v43
	s_waitcnt lgkmcnt(10)
	v_pk_add_f32 v[44:45], v[44:45], v[50:51]
	ds_bpermute_b32 v50, v3, v40
	ds_bpermute_b32 v51, v3, v41
	ds_bpermute_b32 v52, v80, v38
	ds_bpermute_b32 v53, v80, v39
	ds_bpermute_b32 v54, v3, v36
	ds_bpermute_b32 v55, v3, v37
	s_waitcnt lgkmcnt(14)
	v_pk_add_f32 v[28:29], v[30:31], v[60:61]
	s_waitcnt lgkmcnt(12)
	v_pk_add_f32 v[60:61], v[62:63], v[64:65]
	s_waitcnt lgkmcnt(10)
	v_pk_add_f32 v[62:63], v[24:25], v[66:67]
	ds_bpermute_b32 v66, v3, v22
	ds_bpermute_b32 v67, v3, v23
	ds_bpermute_b32 v68, v3, v20
	ds_bpermute_b32 v69, v3, v21
	ds_bpermute_b32 v70, v3, v18
	ds_bpermute_b32 v71, v3, v19
	ds_bpermute_b32 v72, v80, v16
	ds_bpermute_b32 v73, v80, v17
	ds_bpermute_b32 v74, v3, v14
	ds_bpermute_b32 v75, v3, v15
	ds_bpermute_b32 v76, v3, v12
	ds_bpermute_b32 v77, v3, v13
	ds_bpermute_b32 v78, v3, v10
	ds_bpermute_b32 v79, v3, v11
	s_waitcnt lgkmcnt(14)
	v_pk_add_f32 v[8:9], v[46:47], v[8:9]
	v_pk_add_f32 v[42:43], v[42:43], v[48:49]
	v_pk_add_f32 v[40:41], v[40:41], v[50:51]
	v_pk_add_f32 v[38:39], v[38:39], v[52:53]
	v_pk_add_f32 v[52:53], v[36:37], v[54:55]
	s_waitcnt lgkmcnt(12)
	v_pk_add_f32 v[22:23], v[22:23], v[66:67]
	s_waitcnt lgkmcnt(10)
	v_pk_add_f32 v[20:21], v[20:21], v[68:69]
	s_waitcnt lgkmcnt(8)
	v_pk_add_f32 v[18:19], v[18:19], v[70:71]
	s_waitcnt lgkmcnt(6)
	v_pk_add_f32 v[16:17], v[16:17], v[72:73]
	s_waitcnt lgkmcnt(4)
	v_pk_add_f32 v[72:73], v[14:15], v[74:75]
	s_waitcnt lgkmcnt(2)
	v_pk_add_f32 v[12:13], v[12:13], v[76:77]
	s_waitcnt lgkmcnt(0)
	v_pk_add_f32 v[78:79], v[10:11], v[78:79]
	ds_bpermute_b32 v46, v80, v8
	ds_bpermute_b32 v47, v80, v9
	ds_bpermute_b32 v48, v80, v42
	ds_bpermute_b32 v49, v80, v43
	ds_bpermute_b32 v50, v80, v40
	ds_bpermute_b32 v51, v80, v41
	ds_bpermute_b32 v54, v80, v52
	ds_bpermute_b32 v55, v80, v53
	ds_bpermute_b32 v64, v80, v62
	ds_bpermute_b32 v65, v80, v63
	ds_bpermute_b32 v66, v80, v22
	ds_bpermute_b32 v67, v80, v23
	ds_bpermute_b32 v68, v80, v20
	ds_bpermute_b32 v69, v80, v21
	ds_bpermute_b32 v70, v80, v18
	ds_bpermute_b32 v71, v80, v19
	ds_bpermute_b32 v74, v80, v72
	ds_bpermute_b32 v75, v80, v73
	ds_bpermute_b32 v76, v80, v12
	ds_bpermute_b32 v77, v80, v13
	ds_bpermute_b32 v84, v80, v78
	ds_bpermute_b32 v85, v80, v79
	s_waitcnt lgkmcnt(14)
	v_pk_add_f32 v[8:9], v[8:9], v[46:47]
	v_pk_add_f32 v[42:43], v[42:43], v[48:49]
	v_pk_add_f32 v[40:41], v[40:41], v[50:51]
	v_pk_add_f32 v[52:53], v[52:53], v[54:55]
	s_waitcnt lgkmcnt(12)
	v_pk_add_f32 v[62:63], v[62:63], v[64:65]
	s_waitcnt lgkmcnt(10)
	v_pk_add_f32 v[22:23], v[22:23], v[66:67]
	s_waitcnt lgkmcnt(8)
	v_pk_add_f32 v[20:21], v[20:21], v[68:69]
	s_waitcnt lgkmcnt(6)
	v_pk_add_f32 v[18:19], v[18:19], v[70:71]
	s_waitcnt lgkmcnt(4)
	v_pk_add_f32 v[72:73], v[72:73], v[74:75]
	s_waitcnt lgkmcnt(2)
	v_pk_add_f32 v[10:11], v[12:13], v[76:77]
	s_waitcnt lgkmcnt(0)
	v_pk_add_f32 v[76:77], v[78:79], v[84:85]
	ds_bpermute_b32 v26, v81, v8
	ds_bpermute_b32 v27, v81, v9
	ds_bpermute_b32 v46, v81, v44
	ds_bpermute_b32 v47, v81, v45
	ds_bpermute_b32 v48, v81, v42
	ds_bpermute_b32 v49, v81, v43
	ds_bpermute_b32 v50, v81, v40
	ds_bpermute_b32 v51, v81, v41
	ds_bpermute_b32 v36, v81, v38
	ds_bpermute_b32 v37, v81, v39
	ds_bpermute_b32 v54, v81, v52
	ds_bpermute_b32 v55, v81, v53
	ds_bpermute_b32 v34, v81, v32
	ds_bpermute_b32 v35, v81, v33
	ds_bpermute_b32 v58, v81, v56
	ds_bpermute_b32 v59, v81, v57
	ds_bpermute_b32 v30, v81, v28
	ds_bpermute_b32 v31, v81, v29
	ds_bpermute_b32 v24, v81, v60
	ds_bpermute_b32 v25, v81, v61
	ds_bpermute_b32 v64, v81, v62
	ds_bpermute_b32 v65, v81, v63
	ds_bpermute_b32 v66, v81, v22
	ds_bpermute_b32 v67, v81, v23
	ds_bpermute_b32 v68, v81, v20
	ds_bpermute_b32 v69, v81, v21
	ds_bpermute_b32 v70, v81, v18
	ds_bpermute_b32 v71, v81, v19
	ds_bpermute_b32 v14, v81, v16
	ds_bpermute_b32 v15, v81, v17
	ds_bpermute_b32 v74, v81, v72
	ds_bpermute_b32 v75, v81, v73
	ds_bpermute_b32 v12, v81, v10
	ds_bpermute_b32 v13, v81, v11
	ds_bpermute_b32 v78, v81, v76
	ds_bpermute_b32 v79, v81, v77
	s_and_saveexec_b64 s[8:9], vcc
	s_cbranch_execz .LBB0_386
	s_waitcnt lgkmcnt(14)
	v_pk_add_f32 v[84:85], v[8:9], v[26:27]
	v_pk_add_f32 v[26:27], v[28:29], v[30:31]
	v_pk_add_f32 v[28:29], v[60:61], v[24:25]
	v_pk_add_f32 v[86:87], v[44:45], v[46:47]
	v_pk_add_f32 v[42:43], v[42:43], v[48:49]
	v_pk_add_f32 v[44:45], v[40:41], v[50:51]
	v_pk_add_f32 v[36:37], v[38:39], v[36:37]
	v_pk_add_f32 v[38:39], v[52:53], v[54:55]
	v_pk_add_f32 v[32:33], v[32:33], v[34:35]
	v_pk_add_f32 v[34:35], v[56:57], v[58:59]
	ds_write_b128 v5, v[26:29] offset:512
	v_pk_add_f32 v[24:25], v[62:63], v[64:65]
	s_waitcnt lgkmcnt(13)
	v_pk_add_f32 v[26:27], v[22:23], v[66:67]
	s_waitcnt lgkmcnt(11)
	v_pk_add_f32 v[20:21], v[20:21], v[68:69]
	s_waitcnt lgkmcnt(9)
	v_pk_add_f32 v[22:23], v[18:19], v[70:71]
	s_waitcnt lgkmcnt(7)
	v_pk_add_f32 v[14:15], v[16:17], v[14:15]
	s_waitcnt lgkmcnt(5)
	v_pk_add_f32 v[16:17], v[72:73], v[74:75]
	s_waitcnt lgkmcnt(3)
	v_pk_add_f32 v[8:9], v[10:11], v[12:13]
	s_waitcnt lgkmcnt(1)
	v_pk_add_f32 v[10:11], v[76:77], v[78:79]
	ds_write_b128 v5, v[84:87]
	ds_write_b128 v5, v[42:45] offset:128
	ds_write_b128 v5, v[36:39] offset:256
	ds_write_b128 v5, v[32:35] offset:384
	ds_write_b128 v5, v[24:27] offset:640
	ds_write_b128 v5, v[20:23] offset:768
	ds_write_b128 v5, v[14:17] offset:896
	ds_write_b128 v5, v[8:11] offset:1024
